# peel first K-loop iteration of all five GEMMs with C=0 first-touch MFMAs (drops 128 accumulator-zeroing VALU per tile)
# speedup vs baseline: 1.0017x; 1.0005x over previous
.LBB0_675:
	s_ashr_i32 s21, s20, 31
	s_lshl_b64 s[8:9], s[20:21], 19
	s_add_u32 s26, s36, s8
	s_addc_u32 s27, s37, s9
	s_and_b64 s[8:9], s[6:7], exec
	s_cselect_b32 s21, s27, s69
	s_cselect_b32 s31, s26, s68
	s_ashr_i32 s11, s10, 31
	s_lshl_b64 s[8:9], s[10:11], 19
	s_add_u32 s52, s40, s8
	s_addc_u32 s53, s60, s9
	s_and_b64 s[8:9], s[6:7], exec
	s_cselect_b32 s11, s53, s57
	s_cselect_b32 s82, s52, s56
	s_add_u32 s8, s68, 0x40080
	s_addc_u32 s9, s69, 0
	s_add_u32 s83, s56, 0x100
	s_addc_u32 s84, s57, 0
	s_mov_b32 s85, -2
	s_add_u32 s56, s8, 0xfffc0080
	s_addc_u32 s57, s9, -1
	s_add_i32 s64, 0, 0x10000
	s_cmp_eq_u32 s85, 12
	s_cselect_b32 s69, s21, s57
	s_cselect_b32 s68, s31, s56
	v_add_u32_e32 v160, s64, v163
	s_cselect_b32 s57, s11, s84
	s_cselect_b32 s56, s82, s83
	s_add_i32 s86, 0, 0x14000
	ds_read_b128 v[148:151], v160
	ds_read_b128 v[152:155], v160 offset:1024
	ds_read_b128 v[156:159], v160 offset:2048
	ds_read_b128 v[166:169], v160 offset:3072
	v_add_u32_e32 v160, s86, v163
	ds_read_b128 v[170:173], v160
	ds_read_b128 v[174:177], v160 offset:1024
	ds_read_b128 v[178:181], v160 offset:2048
	ds_read_b128 v[182:185], v160 offset:3072
	v_lshl_add_u64 v[160:161], s[8:9], 0, v[144:145]
	s_add_i32 m0, s72, 0xc000
	ds_read_b128 v[186:189], v165
	ds_read_b128 v[190:193], v165 offset:1024
	ds_read_b128 v[194:197], v165 offset:2048
	ds_read_b128 v[198:201], v165 offset:3072
	ds_read_b128 v[202:205], v165 offset:4096
	ds_read_b128 v[206:209], v165 offset:5120
	ds_read_b128 v[222:225], v165 offset:6144
	ds_read_b128 v[226:229], v165 offset:7168
	global_load_lds_dwordx4 v[160:161], off
	v_lshl_add_u64 v[160:161], s[8:9], 0, v[146:147]
	s_add_i32 m0, s72, 0xe000
	s_nop 0
	global_load_lds_dwordx4 v[160:161], off
	s_waitcnt vmcnt(8)
	s_waitcnt lgkmcnt(0)
	s_barrier
	s_setprio 1
	s_waitcnt lgkmcnt(0)
	v_mfma_f32_16x16x32_bf16 v[70:73], v[148:151], v[186:189], 0
	v_mfma_f32_16x16x32_bf16 v[66:69], v[156:159], v[186:189], 0
	v_mfma_f32_16x16x32_bf16 v[54:57], v[148:151], v[194:197], 0
	v_mfma_f32_16x16x32_bf16 v[50:53], v[156:159], v[194:197], 0
	v_mfma_f32_16x16x32_bf16 v[46:49], v[148:151], v[202:205], 0
	v_mfma_f32_16x16x32_bf16 v[42:45], v[156:159], v[202:205], 0
	v_mfma_f32_16x16x32_bf16 v[38:41], v[148:151], v[222:225], 0
	v_mfma_f32_16x16x32_bf16 v[34:37], v[156:159], v[222:225], 0
	v_mfma_f32_16x16x32_bf16 v[70:73], v[152:155], v[190:193], v[70:73]
	v_mfma_f32_16x16x32_bf16 v[66:69], v[166:169], v[190:193], v[66:69]
	v_mfma_f32_16x16x32_bf16 v[54:57], v[152:155], v[198:201], v[54:57]
	v_mfma_f32_16x16x32_bf16 v[50:53], v[166:169], v[198:201], v[50:53]
	v_mfma_f32_16x16x32_bf16 v[46:49], v[152:155], v[206:209], v[46:49]
	v_mfma_f32_16x16x32_bf16 v[42:45], v[166:169], v[206:209], v[42:45]
	v_mfma_f32_16x16x32_bf16 v[38:41], v[152:155], v[226:229], v[38:41]
	v_mfma_f32_16x16x32_bf16 v[34:37], v[166:169], v[226:229], v[34:37]
	s_setprio 0
	s_setprio 1
	v_mfma_f32_16x16x32_bf16 v[126:129], v[170:173], v[186:189], 0
	v_mfma_f32_16x16x32_bf16 v[122:125], v[178:181], v[186:189], 0
	v_mfma_f32_16x16x32_bf16 v[118:121], v[170:173], v[194:197], 0
	v_mfma_f32_16x16x32_bf16 v[114:117], v[178:181], v[194:197], 0
	v_mfma_f32_16x16x32_bf16 v[110:113], v[170:173], v[202:205], 0
	v_mfma_f32_16x16x32_bf16 v[106:109], v[178:181], v[202:205], 0
	v_mfma_f32_16x16x32_bf16 v[102:105], v[170:173], v[222:225], 0
	v_mfma_f32_16x16x32_bf16 v[98:101], v[178:181], v[222:225], 0
	v_mfma_f32_16x16x32_bf16 v[126:129], v[174:177], v[190:193], v[126:129]
	v_mfma_f32_16x16x32_bf16 v[122:125], v[182:185], v[190:193], v[122:125]
	v_mfma_f32_16x16x32_bf16 v[118:121], v[174:177], v[198:201], v[118:121]
	v_mfma_f32_16x16x32_bf16 v[114:117], v[182:185], v[198:201], v[114:117]
	v_mfma_f32_16x16x32_bf16 v[110:113], v[174:177], v[206:209], v[110:113]
	v_mfma_f32_16x16x32_bf16 v[106:109], v[182:185], v[206:209], v[106:109]
	v_mfma_f32_16x16x32_bf16 v[102:105], v[174:177], v[226:229], v[102:105]
	v_mfma_f32_16x16x32_bf16 v[98:101], v[182:185], v[226:229], v[98:101]
	s_setprio 0
	s_barrier
	s_add_i32 s64, s64, s63
	v_lshl_add_u64 v[160:161], s[56:57], 0, v[0:1]
	s_mov_b32 m0, s64
	ds_read_b128 v[186:189], v165 offset:16384
	ds_read_b128 v[190:193], v165 offset:17408
	ds_read_b128 v[194:197], v165 offset:18432
	ds_read_b128 v[198:201], v165 offset:19456
	ds_read_b128 v[202:205], v165 offset:20480
	ds_read_b128 v[206:209], v165 offset:21504
	ds_read_b128 v[222:225], v165 offset:22528
	ds_read_b128 v[226:229], v165 offset:23552
	global_load_lds_dwordx4 v[160:161], off
	s_add_i32 m0, s64, 0x2000
	s_add_u32 s64, s56, 0x40000
	v_lshl_add_u64 v[210:211], s[56:57], 0, v[134:135]
	s_addc_u32 s65, s57, 0
	s_add_i32 s86, s86, s63
	global_load_lds_dwordx4 v[210:211], off
	v_lshl_add_u64 v[230:231], s[64:65], 0, v[0:1]
	s_mov_b32 m0, s86
	v_lshl_add_u64 v[232:233], s[68:69], 0, v[136:137]
	global_load_lds_dwordx4 v[230:231], off
	v_lshl_add_u64 v[230:231], s[64:65], 0, v[134:135]
	s_add_i32 m0, s86, 0x2000
	s_nop 0
	global_load_lds_dwordx4 v[230:231], off
	v_lshl_add_u64 v[230:231], s[68:69], 0, v[138:139]
	s_mov_b32 m0, s72
	s_nop 0
	global_load_lds_dwordx4 v[230:231], off
	s_mov_b32 m0, s73
	s_nop 0
	global_load_lds_dwordx4 v[232:233], off
	s_waitcnt vmcnt(8)
	s_waitcnt lgkmcnt(0)
	s_barrier
	s_setprio 1
	s_waitcnt lgkmcnt(0)
	v_mfma_f32_16x16x32_bf16 v[30:33], v[148:151], v[186:189], 0
	v_mfma_f32_16x16x32_bf16 v[26:29], v[156:159], v[186:189], 0
	v_mfma_f32_16x16x32_bf16 v[22:25], v[148:151], v[194:197], 0
	v_mfma_f32_16x16x32_bf16 v[18:21], v[156:159], v[194:197], 0
	v_mfma_f32_16x16x32_bf16 v[14:17], v[148:151], v[202:205], 0
	v_mfma_f32_16x16x32_bf16 v[10:13], v[156:159], v[202:205], 0
	v_mfma_f32_16x16x32_bf16 v[6:9], v[148:151], v[222:225], 0
	v_mfma_f32_16x16x32_bf16 v[2:5], v[156:159], v[222:225], 0
	v_mfma_f32_16x16x32_bf16 v[30:33], v[152:155], v[190:193], v[30:33]
	v_mfma_f32_16x16x32_bf16 v[26:29], v[166:169], v[190:193], v[26:29]
	v_mfma_f32_16x16x32_bf16 v[22:25], v[152:155], v[198:201], v[22:25]
	v_mfma_f32_16x16x32_bf16 v[18:21], v[166:169], v[198:201], v[18:21]
	v_mfma_f32_16x16x32_bf16 v[14:17], v[152:155], v[206:209], v[14:17]
	v_mfma_f32_16x16x32_bf16 v[10:13], v[166:169], v[206:209], v[10:13]
	v_mfma_f32_16x16x32_bf16 v[6:9], v[152:155], v[226:229], v[6:9]
	v_mfma_f32_16x16x32_bf16 v[2:5], v[166:169], v[226:229], v[2:5]
	s_setprio 0
	s_setprio 1
	v_mfma_f32_16x16x32_bf16 v[94:97], v[170:173], v[186:189], 0
	v_mfma_f32_16x16x32_bf16 v[90:93], v[178:181], v[186:189], 0
	v_mfma_f32_16x16x32_bf16 v[86:89], v[170:173], v[194:197], 0
	v_mfma_f32_16x16x32_bf16 v[82:85], v[178:181], v[194:197], 0
	v_mfma_f32_16x16x32_bf16 v[78:81], v[170:173], v[202:205], 0
	v_mfma_f32_16x16x32_bf16 v[74:77], v[178:181], v[202:205], 0
	v_mfma_f32_16x16x32_bf16 v[62:65], v[170:173], v[222:225], 0
	v_mfma_f32_16x16x32_bf16 v[58:61], v[178:181], v[222:225], 0
	v_mfma_f32_16x16x32_bf16 v[94:97], v[174:177], v[190:193], v[94:97]
	v_mfma_f32_16x16x32_bf16 v[90:93], v[182:185], v[190:193], v[90:93]
	v_mfma_f32_16x16x32_bf16 v[86:89], v[174:177], v[198:201], v[86:89]
	v_mfma_f32_16x16x32_bf16 v[82:85], v[182:185], v[198:201], v[82:85]
	v_mfma_f32_16x16x32_bf16 v[78:81], v[174:177], v[206:209], v[78:81]
	v_mfma_f32_16x16x32_bf16 v[74:77], v[182:185], v[206:209], v[74:77]
	v_mfma_f32_16x16x32_bf16 v[62:65], v[174:177], v[226:229], v[62:65]
	v_mfma_f32_16x16x32_bf16 v[58:61], v[182:185], v[226:229], v[58:61]
	s_setprio 0
	s_barrier
	s_add_i32 s86, 0, 0x18000
	s_add_i32 s87, 0, 0x1c000
	v_add_u32_e32 v166, s86, v163
	v_add_u32_e32 v182, s87, v163
	ds_read_b128 v[148:151], v166
	ds_read_b128 v[152:155], v166 offset:1024
	ds_read_b128 v[156:159], v166 offset:2048
	ds_read_b128 v[166:169], v166 offset:3072
	ds_read_b128 v[170:173], v182
	ds_read_b128 v[174:177], v182 offset:1024
	ds_read_b128 v[178:181], v182 offset:2048
	ds_read_b128 v[182:185], v182 offset:3072
	s_add_u32 s64, s68, 0x40000
	s_addc_u32 s65, s69, 0
	s_mov_b32 m0, s74
	v_lshl_add_u64 v[234:235], s[64:65], 0, v[138:139]
	ds_read_b128 v[186:189], v165 offset:32768
	ds_read_b128 v[190:193], v165 offset:33792
	ds_read_b128 v[194:197], v165 offset:34816
	ds_read_b128 v[198:201], v165 offset:35840
	ds_read_b128 v[202:205], v165 offset:36864
	ds_read_b128 v[206:209], v165 offset:37888
	ds_read_b128 v[222:225], v165 offset:38912
	ds_read_b128 v[226:229], v165 offset:39936
	global_load_lds_dwordx4 v[234:235], off
	v_lshl_add_u64 v[234:235], s[64:65], 0, v[136:137]
	s_mov_b32 m0, s75
	s_nop 0
	global_load_lds_dwordx4 v[234:235], off
	s_waitcnt vmcnt(8)
	s_waitcnt lgkmcnt(0)
	s_barrier
	s_setprio 1
	s_waitcnt lgkmcnt(0)
	v_mfma_f32_16x16x32_bf16 v[70:73], v[148:151], v[186:189], v[70:73]
	v_mfma_f32_16x16x32_bf16 v[66:69], v[156:159], v[186:189], v[66:69]
	v_mfma_f32_16x16x32_bf16 v[54:57], v[148:151], v[194:197], v[54:57]
	v_mfma_f32_16x16x32_bf16 v[50:53], v[156:159], v[194:197], v[50:53]
	v_mfma_f32_16x16x32_bf16 v[46:49], v[148:151], v[202:205], v[46:49]
	v_mfma_f32_16x16x32_bf16 v[42:45], v[156:159], v[202:205], v[42:45]
	v_mfma_f32_16x16x32_bf16 v[38:41], v[148:151], v[222:225], v[38:41]
	v_mfma_f32_16x16x32_bf16 v[34:37], v[156:159], v[222:225], v[34:37]
	v_mfma_f32_16x16x32_bf16 v[70:73], v[152:155], v[190:193], v[70:73]
	v_mfma_f32_16x16x32_bf16 v[66:69], v[166:169], v[190:193], v[66:69]
	v_mfma_f32_16x16x32_bf16 v[54:57], v[152:155], v[198:201], v[54:57]
	v_mfma_f32_16x16x32_bf16 v[50:53], v[166:169], v[198:201], v[50:53]
	v_mfma_f32_16x16x32_bf16 v[46:49], v[152:155], v[206:209], v[46:49]
	v_mfma_f32_16x16x32_bf16 v[42:45], v[166:169], v[206:209], v[42:45]
	v_mfma_f32_16x16x32_bf16 v[38:41], v[152:155], v[226:229], v[38:41]
	v_mfma_f32_16x16x32_bf16 v[34:37], v[166:169], v[226:229], v[34:37]
	s_setprio 0
	s_setprio 1
	v_mfma_f32_16x16x32_bf16 v[126:129], v[170:173], v[186:189], v[126:129]
	v_mfma_f32_16x16x32_bf16 v[122:125], v[178:181], v[186:189], v[122:125]
	v_mfma_f32_16x16x32_bf16 v[118:121], v[170:173], v[194:197], v[118:121]
	v_mfma_f32_16x16x32_bf16 v[114:117], v[178:181], v[194:197], v[114:117]
	v_mfma_f32_16x16x32_bf16 v[110:113], v[170:173], v[202:205], v[110:113]
	v_mfma_f32_16x16x32_bf16 v[106:109], v[178:181], v[202:205], v[106:109]
	v_mfma_f32_16x16x32_bf16 v[102:105], v[170:173], v[222:225], v[102:105]
	v_mfma_f32_16x16x32_bf16 v[98:101], v[178:181], v[222:225], v[98:101]
	v_mfma_f32_16x16x32_bf16 v[126:129], v[174:177], v[190:193], v[126:129]
	v_mfma_f32_16x16x32_bf16 v[122:125], v[182:185], v[190:193], v[122:125]
	v_mfma_f32_16x16x32_bf16 v[118:121], v[174:177], v[198:201], v[118:121]
	v_mfma_f32_16x16x32_bf16 v[114:117], v[182:185], v[198:201], v[114:117]
	v_mfma_f32_16x16x32_bf16 v[110:113], v[174:177], v[206:209], v[110:113]
	v_mfma_f32_16x16x32_bf16 v[106:109], v[182:185], v[206:209], v[106:109]
	v_mfma_f32_16x16x32_bf16 v[102:105], v[174:177], v[226:229], v[102:105]
	v_mfma_f32_16x16x32_bf16 v[98:101], v[182:185], v[226:229], v[98:101]
	s_setprio 0
	s_barrier
	s_add_i32 s64, s86, s63
	v_lshl_add_u64 v[160:161], v[160:161], 0, s[48:49]
	s_mov_b32 m0, s64
	ds_read_b128 v[186:189], v165 offset:49152
	ds_read_b128 v[190:193], v165 offset:50176
	ds_read_b128 v[194:197], v165 offset:51200
	ds_read_b128 v[198:201], v165 offset:52224
	ds_read_b128 v[202:205], v165 offset:53248
	ds_read_b128 v[206:209], v165 offset:54272
	ds_read_b128 v[222:225], v165 offset:55296
	ds_read_b128 v[226:229], v165 offset:56320
	global_load_lds_dwordx4 v[160:161], off
	s_add_i32 m0, s64, 0x2000
	s_add_u32 s56, s56, 0x40080
	v_lshl_add_u64 v[160:161], v[210:211], 0, s[48:49]
	s_addc_u32 s57, s57, 0
	s_add_i32 s64, s87, s63
	global_load_lds_dwordx4 v[160:161], off
	v_lshl_add_u64 v[160:161], s[56:57], 0, v[0:1]
	s_mov_b32 m0, s64
	s_nop 0
	global_load_lds_dwordx4 v[160:161], off
	v_lshl_add_u64 v[160:161], s[56:57], 0, v[134:135]
	s_add_i32 m0, s64, 0x2000
	s_nop 0
	global_load_lds_dwordx4 v[160:161], off
	v_lshl_add_u64 v[160:161], v[230:231], 0, s[48:49]
	s_mov_b32 m0, s78
	s_nop 0
	global_load_lds_dwordx4 v[160:161], off
	v_lshl_add_u64 v[160:161], v[232:233], 0, s[48:49]
	s_mov_b32 m0, s79
	s_nop 0
	global_load_lds_dwordx4 v[160:161], off
	s_waitcnt vmcnt(8)
	s_waitcnt lgkmcnt(0)
	s_barrier
	s_setprio 1
	s_waitcnt lgkmcnt(0)
	v_mfma_f32_16x16x32_bf16 v[30:33], v[148:151], v[186:189], v[30:33]
	v_mfma_f32_16x16x32_bf16 v[26:29], v[156:159], v[186:189], v[26:29]
	v_mfma_f32_16x16x32_bf16 v[22:25], v[148:151], v[194:197], v[22:25]
	v_mfma_f32_16x16x32_bf16 v[18:21], v[156:159], v[194:197], v[18:21]
	v_mfma_f32_16x16x32_bf16 v[14:17], v[148:151], v[202:205], v[14:17]
	v_mfma_f32_16x16x32_bf16 v[10:13], v[156:159], v[202:205], v[10:13]
	v_mfma_f32_16x16x32_bf16 v[6:9], v[148:151], v[222:225], v[6:9]
	v_mfma_f32_16x16x32_bf16 v[2:5], v[156:159], v[222:225], v[2:5]
	v_mfma_f32_16x16x32_bf16 v[30:33], v[152:155], v[190:193], v[30:33]
	v_mfma_f32_16x16x32_bf16 v[26:29], v[166:169], v[190:193], v[26:29]
	v_mfma_f32_16x16x32_bf16 v[22:25], v[152:155], v[198:201], v[22:25]
	v_mfma_f32_16x16x32_bf16 v[18:21], v[166:169], v[198:201], v[18:21]
	v_mfma_f32_16x16x32_bf16 v[14:17], v[152:155], v[206:209], v[14:17]
	v_mfma_f32_16x16x32_bf16 v[10:13], v[166:169], v[206:209], v[10:13]
	v_mfma_f32_16x16x32_bf16 v[6:9], v[152:155], v[226:229], v[6:9]
	v_mfma_f32_16x16x32_bf16 v[2:5], v[166:169], v[226:229], v[2:5]
	s_setprio 0
	s_setprio 1
	v_mfma_f32_16x16x32_bf16 v[94:97], v[170:173], v[186:189], v[94:97]
	v_mfma_f32_16x16x32_bf16 v[90:93], v[178:181], v[186:189], v[90:93]
	v_mfma_f32_16x16x32_bf16 v[86:89], v[170:173], v[194:197], v[86:89]
	v_mfma_f32_16x16x32_bf16 v[82:85], v[178:181], v[194:197], v[82:85]
	v_mfma_f32_16x16x32_bf16 v[78:81], v[170:173], v[202:205], v[78:81]
	v_mfma_f32_16x16x32_bf16 v[74:77], v[178:181], v[202:205], v[74:77]
	v_mfma_f32_16x16x32_bf16 v[62:65], v[170:173], v[222:225], v[62:65]
	v_mfma_f32_16x16x32_bf16 v[58:61], v[178:181], v[222:225], v[58:61]
	v_mfma_f32_16x16x32_bf16 v[94:97], v[174:177], v[190:193], v[94:97]
	v_mfma_f32_16x16x32_bf16 v[90:93], v[182:185], v[190:193], v[90:93]
	v_mfma_f32_16x16x32_bf16 v[86:89], v[174:177], v[198:201], v[86:89]
	v_mfma_f32_16x16x32_bf16 v[82:85], v[182:185], v[198:201], v[82:85]
	v_mfma_f32_16x16x32_bf16 v[78:81], v[174:177], v[206:209], v[78:81]
	v_mfma_f32_16x16x32_bf16 v[74:77], v[182:185], v[206:209], v[74:77]
	v_mfma_f32_16x16x32_bf16 v[62:65], v[174:177], v[226:229], v[62:65]
	v_mfma_f32_16x16x32_bf16 v[58:61], v[182:185], v[226:229], v[58:61]
	s_setprio 0
	s_barrier
	s_add_i32 s85, s85, 2
	s_add_u32 s8, s8, 0x100
	s_addc_u32 s9, s9, 0
	s_add_u32 s83, s83, 0x100
	s_addc_u32 s84, s84, 0

.LBB0_1458:
	s_ashr_i32 s11, s12, 3
	s_add_i32 s11, s12, s11
	s_and_b64 s[16:17], s[66:67], s[4:5]
	s_add_i32 s11, s11, 1
	s_and_b64 s[16:17], s[16:17], exec
	s_cselect_b32 s12, s11, s12
	s_ashr_i32 s13, s12, 31
	s_lshl_b64 s[16:17], s[12:13], 19
	s_add_u32 s16, s37, s16
	s_addc_u32 s17, s60, s17
	s_and_b64 s[18:19], s[4:5], exec
	s_cselect_b32 s13, s17, s53
	s_cselect_b32 s27, s16, s52
	s_ashr_i32 s11, s10, 31
	s_lshl_b64 s[18:19], s[10:11], 19
	s_add_u32 s18, s63, s18
	s_addc_u32 s19, s70, s19
	s_and_b64 s[30:31], s[4:5], exec
	s_cselect_b32 s11, s19, s57
	s_cselect_b32 s30, s18, s56
	s_add_u32 s52, s52, 0x40080
	s_addc_u32 s53, s53, 0
	s_add_u32 s31, s56, 0x100
	s_addc_u32 s84, s57, 0
	s_mov_b32 s85, -2
	s_add_u32 s56, s52, 0xfffc0080
	s_addc_u32 s57, s53, -1
	s_add_i32 s64, 0, 0x10000
	s_cmp_eq_u32 s85, 12
	s_cselect_b32 s69, s13, s57
	s_cselect_b32 s68, s27, s56
	v_add_u32_e32 v0, s64, v167
	s_cselect_b32 s57, s11, s84
	s_cselect_b32 s56, s30, s31
	s_add_i32 s86, 0, 0x14000
	ds_read_b128 v[134:137], v0
	ds_read_b128 v[150:153], v0 offset:1024
	ds_read_b128 v[154:157], v0 offset:2048
	ds_read_b128 v[158:161], v0 offset:3072
	v_add_u32_e32 v0, s86, v167
	ds_read_b128 v[162:165], v0
	ds_read_b128 v[170:173], v0 offset:1024
	ds_read_b128 v[174:177], v0 offset:2048
	ds_read_b128 v[178:181], v0 offset:3072
	v_lshl_add_u64 v[210:211], s[52:53], 0, v[146:147]
	s_add_i32 m0, s21, 0xc000
	ds_read_b128 v[182:185], v169
	ds_read_b128 v[186:189], v169 offset:1024
	ds_read_b128 v[190:193], v169 offset:2048
	ds_read_b128 v[194:197], v169 offset:3072
	ds_read_b128 v[198:201], v169 offset:4096
	ds_read_b128 v[202:205], v169 offset:5120
	ds_read_b128 v[206:209], v169 offset:6144
	ds_read_b128 v[224:227], v169 offset:7168
	global_load_lds_dwordx4 v[210:211], off
	v_lshl_add_u64 v[210:211], s[52:53], 0, v[148:149]
	s_add_i32 m0, s21, 0xe000
	s_nop 0
	global_load_lds_dwordx4 v[210:211], off
	s_waitcnt vmcnt(8)
	s_waitcnt lgkmcnt(0)
	s_barrier
	s_setprio 1
	s_waitcnt lgkmcnt(0)
	v_mfma_f32_16x16x32_bf16 v[126:129], v[134:137], v[182:185], 0
	v_mfma_f32_16x16x32_bf16 v[122:125], v[154:157], v[182:185], 0
	v_mfma_f32_16x16x32_bf16 v[110:113], v[134:137], v[190:193], 0
	v_mfma_f32_16x16x32_bf16 v[106:109], v[154:157], v[190:193], 0
	v_mfma_f32_16x16x32_bf16 v[94:97], v[134:137], v[198:201], 0
	v_mfma_f32_16x16x32_bf16 v[90:93], v[154:157], v[198:201], 0
	v_mfma_f32_16x16x32_bf16 v[78:81], v[134:137], v[206:209], 0
	v_mfma_f32_16x16x32_bf16 v[74:77], v[154:157], v[206:209], 0
	v_mfma_f32_16x16x32_bf16 v[126:129], v[150:153], v[186:189], v[126:129]
	v_mfma_f32_16x16x32_bf16 v[122:125], v[158:161], v[186:189], v[122:125]
	v_mfma_f32_16x16x32_bf16 v[110:113], v[150:153], v[194:197], v[110:113]
	v_mfma_f32_16x16x32_bf16 v[106:109], v[158:161], v[194:197], v[106:109]
	v_mfma_f32_16x16x32_bf16 v[94:97], v[150:153], v[202:205], v[94:97]
	v_mfma_f32_16x16x32_bf16 v[90:93], v[158:161], v[202:205], v[90:93]
	v_mfma_f32_16x16x32_bf16 v[78:81], v[150:153], v[224:227], v[78:81]
	v_mfma_f32_16x16x32_bf16 v[74:77], v[158:161], v[224:227], v[74:77]
	s_setprio 0
	s_setprio 1
	v_mfma_f32_16x16x32_bf16 v[118:121], v[162:165], v[182:185], 0
	v_mfma_f32_16x16x32_bf16 v[114:117], v[174:177], v[182:185], 0
	v_mfma_f32_16x16x32_bf16 v[102:105], v[162:165], v[190:193], 0
	v_mfma_f32_16x16x32_bf16 v[98:101], v[174:177], v[190:193], 0
	v_mfma_f32_16x16x32_bf16 v[86:89], v[162:165], v[198:201], 0
	v_mfma_f32_16x16x32_bf16 v[82:85], v[174:177], v[198:201], 0
	v_mfma_f32_16x16x32_bf16 v[70:73], v[162:165], v[206:209], 0
	v_mfma_f32_16x16x32_bf16 v[66:69], v[174:177], v[206:209], 0
	v_mfma_f32_16x16x32_bf16 v[118:121], v[170:173], v[186:189], v[118:121]
	v_mfma_f32_16x16x32_bf16 v[114:117], v[178:181], v[186:189], v[114:117]
	v_mfma_f32_16x16x32_bf16 v[102:105], v[170:173], v[194:197], v[102:105]
	v_mfma_f32_16x16x32_bf16 v[98:101], v[178:181], v[194:197], v[98:101]
	v_mfma_f32_16x16x32_bf16 v[86:89], v[170:173], v[202:205], v[86:89]
	v_mfma_f32_16x16x32_bf16 v[82:85], v[178:181], v[202:205], v[82:85]
	v_mfma_f32_16x16x32_bf16 v[70:73], v[170:173], v[224:227], v[70:73]
	v_mfma_f32_16x16x32_bf16 v[66:69], v[178:181], v[224:227], v[66:69]
	s_setprio 0
	s_barrier
	s_add_i32 s64, s64, s71
	v_lshl_add_u64 v[210:211], s[56:57], 0, v[142:143]
	s_mov_b32 m0, s64
	ds_read_b128 v[182:185], v169 offset:16384
	ds_read_b128 v[186:189], v169 offset:17408
	ds_read_b128 v[190:193], v169 offset:18432
	ds_read_b128 v[194:197], v169 offset:19456
	ds_read_b128 v[198:201], v169 offset:20480
	ds_read_b128 v[202:205], v169 offset:21504
	ds_read_b128 v[206:209], v169 offset:22528
	ds_read_b128 v[224:227], v169 offset:23552
	global_load_lds_dwordx4 v[210:211], off
	s_add_i32 m0, s64, 0x2000
	s_add_u32 s64, s56, 0x40000
	v_lshl_add_u64 v[228:229], s[56:57], 0, v[138:139]
	s_addc_u32 s65, s57, 0
	s_add_i32 s86, s86, s71
	global_load_lds_dwordx4 v[228:229], off
	v_lshl_add_u64 v[230:231], s[64:65], 0, v[142:143]
	s_mov_b32 m0, s86
	v_lshl_add_u64 v[232:233], s[68:69], 0, v[140:141]
	global_load_lds_dwordx4 v[230:231], off
	v_lshl_add_u64 v[230:231], s[64:65], 0, v[138:139]
	s_add_i32 m0, s86, 0x2000
	s_nop 0
	global_load_lds_dwordx4 v[230:231], off
	v_lshl_add_u64 v[230:231], s[68:69], 0, v[144:145]
	s_mov_b32 m0, s21
	s_nop 0
	global_load_lds_dwordx4 v[230:231], off
	s_mov_b32 m0, s73
	s_nop 0
	global_load_lds_dwordx4 v[232:233], off
	s_waitcnt vmcnt(8)
	s_waitcnt lgkmcnt(0)
	s_barrier
	s_setprio 1
	s_waitcnt lgkmcnt(0)
	v_mfma_f32_16x16x32_bf16 v[62:65], v[134:137], v[182:185], 0
	v_mfma_f32_16x16x32_bf16 v[58:61], v[154:157], v[182:185], 0
	v_mfma_f32_16x16x32_bf16 v[46:49], v[134:137], v[190:193], 0
	v_mfma_f32_16x16x32_bf16 v[42:45], v[154:157], v[190:193], 0
	v_mfma_f32_16x16x32_bf16 v[30:33], v[134:137], v[198:201], 0
	v_mfma_f32_16x16x32_bf16 v[26:29], v[154:157], v[198:201], 0
	v_mfma_f32_16x16x32_bf16 v[14:17], v[134:137], v[206:209], 0
	v_mfma_f32_16x16x32_bf16 v[10:13], v[154:157], v[206:209], 0
	v_mfma_f32_16x16x32_bf16 v[62:65], v[150:153], v[186:189], v[62:65]
	v_mfma_f32_16x16x32_bf16 v[58:61], v[158:161], v[186:189], v[58:61]
	v_mfma_f32_16x16x32_bf16 v[46:49], v[150:153], v[194:197], v[46:49]
	v_mfma_f32_16x16x32_bf16 v[42:45], v[158:161], v[194:197], v[42:45]
	v_mfma_f32_16x16x32_bf16 v[30:33], v[150:153], v[202:205], v[30:33]
	v_mfma_f32_16x16x32_bf16 v[26:29], v[158:161], v[202:205], v[26:29]
	v_mfma_f32_16x16x32_bf16 v[14:17], v[150:153], v[224:227], v[14:17]
	v_mfma_f32_16x16x32_bf16 v[10:13], v[158:161], v[224:227], v[10:13]
	s_setprio 0
	s_setprio 1
	v_mfma_f32_16x16x32_bf16 v[54:57], v[162:165], v[182:185], 0
	v_mfma_f32_16x16x32_bf16 v[50:53], v[174:177], v[182:185], 0
	v_mfma_f32_16x16x32_bf16 v[38:41], v[162:165], v[190:193], 0
	v_mfma_f32_16x16x32_bf16 v[34:37], v[174:177], v[190:193], 0
	v_mfma_f32_16x16x32_bf16 v[22:25], v[162:165], v[198:201], 0
	v_mfma_f32_16x16x32_bf16 v[18:21], v[174:177], v[198:201], 0
	v_mfma_f32_16x16x32_bf16 v[6:9], v[162:165], v[206:209], 0
	v_mfma_f32_16x16x32_bf16 v[2:5], v[174:177], v[206:209], 0
	v_mfma_f32_16x16x32_bf16 v[54:57], v[170:173], v[186:189], v[54:57]
	v_mfma_f32_16x16x32_bf16 v[50:53], v[178:181], v[186:189], v[50:53]
	v_mfma_f32_16x16x32_bf16 v[38:41], v[170:173], v[194:197], v[38:41]
	v_mfma_f32_16x16x32_bf16 v[34:37], v[178:181], v[194:197], v[34:37]
	v_mfma_f32_16x16x32_bf16 v[22:25], v[170:173], v[202:205], v[22:25]
	v_mfma_f32_16x16x32_bf16 v[18:21], v[178:181], v[202:205], v[18:21]
	v_mfma_f32_16x16x32_bf16 v[6:9], v[170:173], v[224:227], v[6:9]
	v_mfma_f32_16x16x32_bf16 v[2:5], v[178:181], v[224:227], v[2:5]
	s_setprio 0
	s_barrier
	s_add_i32 s86, 0, 0x18000
	v_add_u32_e32 v0, s86, v167
	s_add_i32 s87, 0, 0x1c000
	ds_read_b128 v[134:137], v0
	ds_read_b128 v[150:153], v0 offset:1024
	ds_read_b128 v[154:157], v0 offset:2048
	ds_read_b128 v[158:161], v0 offset:3072
	v_add_u32_e32 v0, s87, v167
	ds_read_b128 v[162:165], v0
	ds_read_b128 v[170:173], v0 offset:1024
	ds_read_b128 v[174:177], v0 offset:2048
	ds_read_b128 v[178:181], v0 offset:3072
	s_add_u32 s64, s68, 0x40000
	s_addc_u32 s65, s69, 0
	s_mov_b32 m0, s74
	v_lshl_add_u64 v[234:235], s[64:65], 0, v[144:145]
	ds_read_b128 v[182:185], v169 offset:32768
	ds_read_b128 v[186:189], v169 offset:33792
	ds_read_b128 v[190:193], v169 offset:34816
	ds_read_b128 v[194:197], v169 offset:35840
	ds_read_b128 v[198:201], v169 offset:36864
	ds_read_b128 v[202:205], v169 offset:37888
	ds_read_b128 v[206:209], v169 offset:38912
	ds_read_b128 v[224:227], v169 offset:39936
	global_load_lds_dwordx4 v[234:235], off
	v_lshl_add_u64 v[234:235], s[64:65], 0, v[140:141]
	s_mov_b32 m0, s75
	s_nop 0
	global_load_lds_dwordx4 v[234:235], off
	s_waitcnt vmcnt(8)
	s_waitcnt lgkmcnt(0)
	s_barrier
	s_setprio 1
	s_waitcnt lgkmcnt(0)
	v_mfma_f32_16x16x32_bf16 v[126:129], v[134:137], v[182:185], v[126:129]
	v_mfma_f32_16x16x32_bf16 v[122:125], v[154:157], v[182:185], v[122:125]
	v_mfma_f32_16x16x32_bf16 v[110:113], v[134:137], v[190:193], v[110:113]
	v_mfma_f32_16x16x32_bf16 v[106:109], v[154:157], v[190:193], v[106:109]
	v_mfma_f32_16x16x32_bf16 v[94:97], v[134:137], v[198:201], v[94:97]
	v_mfma_f32_16x16x32_bf16 v[90:93], v[154:157], v[198:201], v[90:93]
	v_mfma_f32_16x16x32_bf16 v[78:81], v[134:137], v[206:209], v[78:81]
	v_mfma_f32_16x16x32_bf16 v[74:77], v[154:157], v[206:209], v[74:77]
	v_mfma_f32_16x16x32_bf16 v[126:129], v[150:153], v[186:189], v[126:129]
	v_mfma_f32_16x16x32_bf16 v[122:125], v[158:161], v[186:189], v[122:125]
	v_mfma_f32_16x16x32_bf16 v[110:113], v[150:153], v[194:197], v[110:113]
	v_mfma_f32_16x16x32_bf16 v[106:109], v[158:161], v[194:197], v[106:109]
	v_mfma_f32_16x16x32_bf16 v[94:97], v[150:153], v[202:205], v[94:97]
	v_mfma_f32_16x16x32_bf16 v[90:93], v[158:161], v[202:205], v[90:93]
	v_mfma_f32_16x16x32_bf16 v[78:81], v[150:153], v[224:227], v[78:81]
	v_mfma_f32_16x16x32_bf16 v[74:77], v[158:161], v[224:227], v[74:77]
	s_setprio 0
	s_setprio 1
	v_mfma_f32_16x16x32_bf16 v[118:121], v[162:165], v[182:185], v[118:121]
	v_mfma_f32_16x16x32_bf16 v[114:117], v[174:177], v[182:185], v[114:117]
	v_mfma_f32_16x16x32_bf16 v[102:105], v[162:165], v[190:193], v[102:105]
	v_mfma_f32_16x16x32_bf16 v[98:101], v[174:177], v[190:193], v[98:101]
	v_mfma_f32_16x16x32_bf16 v[86:89], v[162:165], v[198:201], v[86:89]
	v_mfma_f32_16x16x32_bf16 v[82:85], v[174:177], v[198:201], v[82:85]
	v_mfma_f32_16x16x32_bf16 v[70:73], v[162:165], v[206:209], v[70:73]
	v_mfma_f32_16x16x32_bf16 v[66:69], v[174:177], v[206:209], v[66:69]
	v_mfma_f32_16x16x32_bf16 v[118:121], v[170:173], v[186:189], v[118:121]
	v_mfma_f32_16x16x32_bf16 v[114:117], v[178:181], v[186:189], v[114:117]
	v_mfma_f32_16x16x32_bf16 v[102:105], v[170:173], v[194:197], v[102:105]
	v_mfma_f32_16x16x32_bf16 v[98:101], v[178:181], v[194:197], v[98:101]
	v_mfma_f32_16x16x32_bf16 v[86:89], v[170:173], v[202:205], v[86:89]
	v_mfma_f32_16x16x32_bf16 v[82:85], v[178:181], v[202:205], v[82:85]
	v_mfma_f32_16x16x32_bf16 v[70:73], v[170:173], v[224:227], v[70:73]
	v_mfma_f32_16x16x32_bf16 v[66:69], v[178:181], v[224:227], v[66:69]
	s_setprio 0
	s_barrier
	s_add_i32 s64, s86, s71
	v_lshl_add_u64 v[210:211], v[210:211], 0, s[48:49]
	s_mov_b32 m0, s64
	ds_read_b128 v[182:185], v169 offset:49152
	ds_read_b128 v[186:189], v169 offset:50176
	ds_read_b128 v[190:193], v169 offset:51200
	ds_read_b128 v[194:197], v169 offset:52224
	ds_read_b128 v[198:201], v169 offset:53248
	ds_read_b128 v[202:205], v169 offset:54272
	ds_read_b128 v[206:209], v169 offset:55296
	ds_read_b128 v[224:227], v169 offset:56320
	global_load_lds_dwordx4 v[210:211], off
	s_add_i32 m0, s64, 0x2000
	s_add_u32 s56, s56, 0x40080
	v_lshl_add_u64 v[210:211], v[228:229], 0, s[48:49]
	s_addc_u32 s57, s57, 0
	s_add_i32 s64, s87, s71
	global_load_lds_dwordx4 v[210:211], off
	v_lshl_add_u64 v[210:211], s[56:57], 0, v[142:143]
	s_mov_b32 m0, s64
	s_nop 0
	global_load_lds_dwordx4 v[210:211], off
	v_lshl_add_u64 v[210:211], s[56:57], 0, v[138:139]
	s_add_i32 m0, s64, 0x2000
	s_nop 0
	global_load_lds_dwordx4 v[210:211], off
	v_lshl_add_u64 v[210:211], v[230:231], 0, s[48:49]
	s_mov_b32 m0, s80
	s_nop 0
	global_load_lds_dwordx4 v[210:211], off
	v_lshl_add_u64 v[210:211], v[232:233], 0, s[48:49]
	s_mov_b32 m0, s81
	s_nop 0
	global_load_lds_dwordx4 v[210:211], off
	s_waitcnt vmcnt(8)
	s_waitcnt lgkmcnt(0)
	s_barrier
	s_setprio 1
	s_waitcnt lgkmcnt(0)
	v_mfma_f32_16x16x32_bf16 v[62:65], v[134:137], v[182:185], v[62:65]
	v_mfma_f32_16x16x32_bf16 v[58:61], v[154:157], v[182:185], v[58:61]
	v_mfma_f32_16x16x32_bf16 v[46:49], v[134:137], v[190:193], v[46:49]
	v_mfma_f32_16x16x32_bf16 v[42:45], v[154:157], v[190:193], v[42:45]
	v_mfma_f32_16x16x32_bf16 v[30:33], v[134:137], v[198:201], v[30:33]
	v_mfma_f32_16x16x32_bf16 v[26:29], v[154:157], v[198:201], v[26:29]
	v_mfma_f32_16x16x32_bf16 v[14:17], v[134:137], v[206:209], v[14:17]
	v_mfma_f32_16x16x32_bf16 v[10:13], v[154:157], v[206:209], v[10:13]
	v_mfma_f32_16x16x32_bf16 v[62:65], v[150:153], v[186:189], v[62:65]
	v_mfma_f32_16x16x32_bf16 v[58:61], v[158:161], v[186:189], v[58:61]
	v_mfma_f32_16x16x32_bf16 v[46:49], v[150:153], v[194:197], v[46:49]
	v_mfma_f32_16x16x32_bf16 v[42:45], v[158:161], v[194:197], v[42:45]
	v_mfma_f32_16x16x32_bf16 v[30:33], v[150:153], v[202:205], v[30:33]
	v_mfma_f32_16x16x32_bf16 v[26:29], v[158:161], v[202:205], v[26:29]
	v_mfma_f32_16x16x32_bf16 v[14:17], v[150:153], v[224:227], v[14:17]
	v_mfma_f32_16x16x32_bf16 v[10:13], v[158:161], v[224:227], v[10:13]
	s_setprio 0
	s_setprio 1
	v_mfma_f32_16x16x32_bf16 v[54:57], v[162:165], v[182:185], v[54:57]
	v_mfma_f32_16x16x32_bf16 v[50:53], v[174:177], v[182:185], v[50:53]
	v_mfma_f32_16x16x32_bf16 v[38:41], v[162:165], v[190:193], v[38:41]
	v_mfma_f32_16x16x32_bf16 v[34:37], v[174:177], v[190:193], v[34:37]
	v_mfma_f32_16x16x32_bf16 v[22:25], v[162:165], v[198:201], v[22:25]
	v_mfma_f32_16x16x32_bf16 v[18:21], v[174:177], v[198:201], v[18:21]
	v_mfma_f32_16x16x32_bf16 v[6:9], v[162:165], v[206:209], v[6:9]
	v_mfma_f32_16x16x32_bf16 v[2:5], v[174:177], v[206:209], v[2:5]
	v_mfma_f32_16x16x32_bf16 v[54:57], v[170:173], v[186:189], v[54:57]
	v_mfma_f32_16x16x32_bf16 v[50:53], v[178:181], v[186:189], v[50:53]
	v_mfma_f32_16x16x32_bf16 v[38:41], v[170:173], v[194:197], v[38:41]
	v_mfma_f32_16x16x32_bf16 v[34:37], v[178:181], v[194:197], v[34:37]
	v_mfma_f32_16x16x32_bf16 v[22:25], v[170:173], v[202:205], v[22:25]
	v_mfma_f32_16x16x32_bf16 v[18:21], v[178:181], v[202:205], v[18:21]
	v_mfma_f32_16x16x32_bf16 v[6:9], v[170:173], v[224:227], v[6:9]
	v_mfma_f32_16x16x32_bf16 v[2:5], v[178:181], v[224:227], v[2:5]
	s_setprio 0
	s_barrier
	s_add_i32 s85, s85, 2
	s_add_u32 s52, s52, 0x100
	s_addc_u32 s53, s53, 0
	s_add_u32 s31, s31, 0x100
	s_addc_u32 s84, s84, 0

.LBB0_1532:
	s_ashr_i32 s17, s16, 31
	s_lshl_b64 s[56:57], s[16:17], 18
	s_add_u32 s56, s37, s56
	s_addc_u32 s57, s60, s57
	s_and_b64 s[6:7], s[6:7], exec
	s_cselect_b32 s17, s57, s69
	s_cselect_b32 s19, s56, s68
	s_add_u32 s6, s70, 0x20080
	s_addc_u32 s7, s71, 0
	s_add_u32 s80, s68, 0x100
	s_addc_u32 s81, s69, 0
	s_mov_b32 s82, -2
	s_add_u32 s64, s6, 0xfffe0080
	s_addc_u32 s65, s7, -1
	s_add_i32 s83, 0, 0x10000
	s_cmp_eq_u32 s82, 4
	s_cselect_b32 s71, s53, s65
	s_cselect_b32 s70, s52, s64
	v_add_u32_e32 v144, s83, v147
	s_cselect_b32 s69, s17, s81
	s_cselect_b32 s68, s19, s80
	s_add_i32 s84, 0, 0x14000
	ds_read_b128 v[150:153], v144
	ds_read_b128 v[154:157], v144 offset:1024
	ds_read_b128 v[158:161], v144 offset:2048
	ds_read_b128 v[162:165], v144 offset:3072
	v_add_u32_e32 v144, s84, v147
	ds_read_b128 v[166:169], v144
	ds_read_b128 v[170:173], v144 offset:1024
	ds_read_b128 v[174:177], v144 offset:2048
	ds_read_b128 v[178:181], v144 offset:3072
	v_lshl_add_u64 v[144:145], s[6:7], 0, v[140:141]
	s_add_i32 m0, s21, 0xc000
	ds_read_b128 v[182:185], v149
	ds_read_b128 v[186:189], v149 offset:1024
	ds_read_b128 v[190:193], v149 offset:2048
	ds_read_b128 v[194:197], v149 offset:3072
	ds_read_b128 v[198:201], v149 offset:4096
	ds_read_b128 v[202:205], v149 offset:5120
	ds_read_b128 v[206:209], v149 offset:6144
	ds_read_b128 v[224:227], v149 offset:7168
	global_load_lds_dwordx4 v[144:145], off
	v_lshl_add_u64 v[144:145], s[6:7], 0, v[142:143]
	s_add_i32 m0, s21, 0xe000
	s_nop 0
	global_load_lds_dwordx4 v[144:145], off
	s_waitcnt vmcnt(8)
	s_waitcnt lgkmcnt(0)
	s_barrier
	s_setprio 1
	s_waitcnt lgkmcnt(0)
	v_mfma_f32_16x16x32_bf16 v[126:129], v[150:153], v[182:185], 0
	v_mfma_f32_16x16x32_bf16 v[122:125], v[158:161], v[182:185], 0
	v_mfma_f32_16x16x32_bf16 v[118:121], v[150:153], v[190:193], 0
	v_mfma_f32_16x16x32_bf16 v[110:113], v[158:161], v[190:193], 0
	v_mfma_f32_16x16x32_bf16 v[102:105], v[150:153], v[198:201], 0
	v_mfma_f32_16x16x32_bf16 v[94:97], v[158:161], v[198:201], 0
	v_mfma_f32_16x16x32_bf16 v[86:89], v[150:153], v[206:209], 0
	v_mfma_f32_16x16x32_bf16 v[78:81], v[158:161], v[206:209], 0
	v_mfma_f32_16x16x32_bf16 v[126:129], v[154:157], v[186:189], v[126:129]
	v_mfma_f32_16x16x32_bf16 v[122:125], v[162:165], v[186:189], v[122:125]
	v_mfma_f32_16x16x32_bf16 v[118:121], v[154:157], v[194:197], v[118:121]
	v_mfma_f32_16x16x32_bf16 v[110:113], v[162:165], v[194:197], v[110:113]
	v_mfma_f32_16x16x32_bf16 v[102:105], v[154:157], v[202:205], v[102:105]
	v_mfma_f32_16x16x32_bf16 v[94:97], v[162:165], v[202:205], v[94:97]
	v_mfma_f32_16x16x32_bf16 v[86:89], v[154:157], v[224:227], v[86:89]
	v_mfma_f32_16x16x32_bf16 v[78:81], v[162:165], v[224:227], v[78:81]
	s_setprio 0
	s_setprio 1
	v_mfma_f32_16x16x32_bf16 v[114:117], v[166:169], v[182:185], 0
	v_mfma_f32_16x16x32_bf16 v[106:109], v[174:177], v[182:185], 0
	v_mfma_f32_16x16x32_bf16 v[98:101], v[166:169], v[190:193], 0
	v_mfma_f32_16x16x32_bf16 v[90:93], v[174:177], v[190:193], 0
	v_mfma_f32_16x16x32_bf16 v[82:85], v[166:169], v[198:201], 0
	v_mfma_f32_16x16x32_bf16 v[74:77], v[174:177], v[198:201], 0
	v_mfma_f32_16x16x32_bf16 v[70:73], v[166:169], v[206:209], 0
	v_mfma_f32_16x16x32_bf16 v[66:69], v[174:177], v[206:209], 0
	v_mfma_f32_16x16x32_bf16 v[114:117], v[170:173], v[186:189], v[114:117]
	v_mfma_f32_16x16x32_bf16 v[106:109], v[178:181], v[186:189], v[106:109]
	v_mfma_f32_16x16x32_bf16 v[98:101], v[170:173], v[194:197], v[98:101]
	v_mfma_f32_16x16x32_bf16 v[90:93], v[178:181], v[194:197], v[90:93]
	v_mfma_f32_16x16x32_bf16 v[82:85], v[170:173], v[202:205], v[82:85]
	v_mfma_f32_16x16x32_bf16 v[74:77], v[178:181], v[202:205], v[74:77]
	v_mfma_f32_16x16x32_bf16 v[70:73], v[170:173], v[224:227], v[70:73]
	v_mfma_f32_16x16x32_bf16 v[66:69], v[178:181], v[224:227], v[66:69]
	s_setprio 0
	s_barrier
	s_add_i32 s64, s83, s63
	v_lshl_add_u64 v[144:145], s[68:69], 0, v[0:1]
	s_mov_b32 m0, s64
	ds_read_b128 v[182:185], v149 offset:16384
	ds_read_b128 v[186:189], v149 offset:17408
	ds_read_b128 v[190:193], v149 offset:18432
	ds_read_b128 v[194:197], v149 offset:19456
	ds_read_b128 v[198:201], v149 offset:20480
	ds_read_b128 v[202:205], v149 offset:21504
	ds_read_b128 v[206:209], v149 offset:22528
	ds_read_b128 v[224:227], v149 offset:23552
	global_load_lds_dwordx4 v[144:145], off
	s_add_i32 m0, s64, 0x2000
	s_add_u32 s64, s68, 0x20000
	v_lshl_add_u64 v[210:211], s[68:69], 0, v[134:135]
	s_addc_u32 s65, s69, 0
	s_add_i32 s83, s84, s63
	global_load_lds_dwordx4 v[210:211], off
	v_lshl_add_u64 v[220:221], s[64:65], 0, v[0:1]
	s_mov_b32 m0, s83
	v_lshl_add_u64 v[228:229], s[70:71], 0, v[136:137]
	global_load_lds_dwordx4 v[220:221], off
	v_lshl_add_u64 v[220:221], s[64:65], 0, v[134:135]
	s_add_i32 m0, s83, 0x2000
	s_nop 0
	global_load_lds_dwordx4 v[220:221], off
	v_lshl_add_u64 v[220:221], s[70:71], 0, v[138:139]
	s_mov_b32 m0, s21
	s_nop 0
	global_load_lds_dwordx4 v[220:221], off
	s_mov_b32 m0, s27
	s_nop 0
	global_load_lds_dwordx4 v[228:229], off
	s_waitcnt vmcnt(8)
	s_waitcnt lgkmcnt(0)
	s_barrier
	s_setprio 1
	s_waitcnt lgkmcnt(0)
	v_mfma_f32_16x16x32_bf16 v[62:65], v[150:153], v[182:185], 0
	v_mfma_f32_16x16x32_bf16 v[58:61], v[158:161], v[182:185], 0
	v_mfma_f32_16x16x32_bf16 v[54:57], v[150:153], v[190:193], 0
	v_mfma_f32_16x16x32_bf16 v[46:49], v[158:161], v[190:193], 0
	v_mfma_f32_16x16x32_bf16 v[38:41], v[150:153], v[198:201], 0
	v_mfma_f32_16x16x32_bf16 v[30:33], v[158:161], v[198:201], 0
	v_mfma_f32_16x16x32_bf16 v[22:25], v[150:153], v[206:209], 0
	v_mfma_f32_16x16x32_bf16 v[14:17], v[158:161], v[206:209], 0
	v_mfma_f32_16x16x32_bf16 v[62:65], v[154:157], v[186:189], v[62:65]
	v_mfma_f32_16x16x32_bf16 v[58:61], v[162:165], v[186:189], v[58:61]
	v_mfma_f32_16x16x32_bf16 v[54:57], v[154:157], v[194:197], v[54:57]
	v_mfma_f32_16x16x32_bf16 v[46:49], v[162:165], v[194:197], v[46:49]
	v_mfma_f32_16x16x32_bf16 v[38:41], v[154:157], v[202:205], v[38:41]
	v_mfma_f32_16x16x32_bf16 v[30:33], v[162:165], v[202:205], v[30:33]
	v_mfma_f32_16x16x32_bf16 v[22:25], v[154:157], v[224:227], v[22:25]
	v_mfma_f32_16x16x32_bf16 v[14:17], v[162:165], v[224:227], v[14:17]
	s_setprio 0
	s_setprio 1
	v_mfma_f32_16x16x32_bf16 v[50:53], v[166:169], v[182:185], 0
	v_mfma_f32_16x16x32_bf16 v[42:45], v[174:177], v[182:185], 0
	v_mfma_f32_16x16x32_bf16 v[34:37], v[166:169], v[190:193], 0
	v_mfma_f32_16x16x32_bf16 v[26:29], v[174:177], v[190:193], 0
	v_mfma_f32_16x16x32_bf16 v[18:21], v[166:169], v[198:201], 0
	v_mfma_f32_16x16x32_bf16 v[10:13], v[174:177], v[198:201], 0
	v_mfma_f32_16x16x32_bf16 v[6:9], v[166:169], v[206:209], 0
	v_mfma_f32_16x16x32_bf16 v[2:5], v[174:177], v[206:209], 0
	v_mfma_f32_16x16x32_bf16 v[50:53], v[170:173], v[186:189], v[50:53]
	v_mfma_f32_16x16x32_bf16 v[42:45], v[178:181], v[186:189], v[42:45]
	v_mfma_f32_16x16x32_bf16 v[34:37], v[170:173], v[194:197], v[34:37]
	v_mfma_f32_16x16x32_bf16 v[26:29], v[178:181], v[194:197], v[26:29]
	v_mfma_f32_16x16x32_bf16 v[18:21], v[170:173], v[202:205], v[18:21]
	v_mfma_f32_16x16x32_bf16 v[10:13], v[178:181], v[202:205], v[10:13]
	v_mfma_f32_16x16x32_bf16 v[6:9], v[170:173], v[224:227], v[6:9]
	v_mfma_f32_16x16x32_bf16 v[2:5], v[178:181], v[224:227], v[2:5]
	s_setprio 0
	s_barrier
	s_add_i32 s83, 0, 0x18000
	s_add_i32 s84, 0, 0x1c000
	v_add_u32_e32 v162, s83, v147
	v_add_u32_e32 v178, s84, v147
	ds_read_b128 v[150:153], v162
	ds_read_b128 v[154:157], v162 offset:1024
	ds_read_b128 v[158:161], v162 offset:2048
	ds_read_b128 v[162:165], v162 offset:3072
	ds_read_b128 v[166:169], v178
	ds_read_b128 v[170:173], v178 offset:1024
	ds_read_b128 v[174:177], v178 offset:2048
	ds_read_b128 v[178:181], v178 offset:3072
	s_add_u32 s64, s70, 0x20000
	s_addc_u32 s65, s71, 0
	s_mov_b32 m0, s72
	v_lshl_add_u64 v[230:231], s[64:65], 0, v[138:139]
	ds_read_b128 v[182:185], v149 offset:32768
	ds_read_b128 v[186:189], v149 offset:33792
	ds_read_b128 v[190:193], v149 offset:34816
	ds_read_b128 v[194:197], v149 offset:35840
	ds_read_b128 v[198:201], v149 offset:36864
	ds_read_b128 v[202:205], v149 offset:37888
	ds_read_b128 v[206:209], v149 offset:38912
	ds_read_b128 v[224:227], v149 offset:39936
	global_load_lds_dwordx4 v[230:231], off
	v_lshl_add_u64 v[230:231], s[64:65], 0, v[136:137]
	s_mov_b32 m0, s73
	s_nop 0
	global_load_lds_dwordx4 v[230:231], off
	s_waitcnt vmcnt(8)
	s_waitcnt lgkmcnt(0)
	s_barrier
	s_setprio 1
	s_waitcnt lgkmcnt(0)
	v_mfma_f32_16x16x32_bf16 v[126:129], v[150:153], v[182:185], v[126:129]
	v_mfma_f32_16x16x32_bf16 v[122:125], v[158:161], v[182:185], v[122:125]
	v_mfma_f32_16x16x32_bf16 v[118:121], v[150:153], v[190:193], v[118:121]
	v_mfma_f32_16x16x32_bf16 v[110:113], v[158:161], v[190:193], v[110:113]
	v_mfma_f32_16x16x32_bf16 v[102:105], v[150:153], v[198:201], v[102:105]
	v_mfma_f32_16x16x32_bf16 v[94:97], v[158:161], v[198:201], v[94:97]
	v_mfma_f32_16x16x32_bf16 v[86:89], v[150:153], v[206:209], v[86:89]
	v_mfma_f32_16x16x32_bf16 v[78:81], v[158:161], v[206:209], v[78:81]
	v_mfma_f32_16x16x32_bf16 v[126:129], v[154:157], v[186:189], v[126:129]
	v_mfma_f32_16x16x32_bf16 v[122:125], v[162:165], v[186:189], v[122:125]
	v_mfma_f32_16x16x32_bf16 v[118:121], v[154:157], v[194:197], v[118:121]
	v_mfma_f32_16x16x32_bf16 v[110:113], v[162:165], v[194:197], v[110:113]
	v_mfma_f32_16x16x32_bf16 v[102:105], v[154:157], v[202:205], v[102:105]
	v_mfma_f32_16x16x32_bf16 v[94:97], v[162:165], v[202:205], v[94:97]
	v_mfma_f32_16x16x32_bf16 v[86:89], v[154:157], v[224:227], v[86:89]
	v_mfma_f32_16x16x32_bf16 v[78:81], v[162:165], v[224:227], v[78:81]
	s_setprio 0
	s_setprio 1
	v_mfma_f32_16x16x32_bf16 v[114:117], v[166:169], v[182:185], v[114:117]
	v_mfma_f32_16x16x32_bf16 v[106:109], v[174:177], v[182:185], v[106:109]
	v_mfma_f32_16x16x32_bf16 v[98:101], v[166:169], v[190:193], v[98:101]
	v_mfma_f32_16x16x32_bf16 v[90:93], v[174:177], v[190:193], v[90:93]
	v_mfma_f32_16x16x32_bf16 v[82:85], v[166:169], v[198:201], v[82:85]
	v_mfma_f32_16x16x32_bf16 v[74:77], v[174:177], v[198:201], v[74:77]
	v_mfma_f32_16x16x32_bf16 v[70:73], v[166:169], v[206:209], v[70:73]
	v_mfma_f32_16x16x32_bf16 v[66:69], v[174:177], v[206:209], v[66:69]
	v_mfma_f32_16x16x32_bf16 v[114:117], v[170:173], v[186:189], v[114:117]
	v_mfma_f32_16x16x32_bf16 v[106:109], v[178:181], v[186:189], v[106:109]
	v_mfma_f32_16x16x32_bf16 v[98:101], v[170:173], v[194:197], v[98:101]
	v_mfma_f32_16x16x32_bf16 v[90:93], v[178:181], v[194:197], v[90:93]
	v_mfma_f32_16x16x32_bf16 v[82:85], v[170:173], v[202:205], v[82:85]
	v_mfma_f32_16x16x32_bf16 v[74:77], v[178:181], v[202:205], v[74:77]
	v_mfma_f32_16x16x32_bf16 v[70:73], v[170:173], v[224:227], v[70:73]
	v_mfma_f32_16x16x32_bf16 v[66:69], v[178:181], v[224:227], v[66:69]
	s_setprio 0
	s_barrier
	s_add_i32 s64, s83, s63
	v_lshl_add_u64 v[144:145], v[144:145], 0, s[48:49]
	s_mov_b32 m0, s64
	ds_read_b128 v[182:185], v149 offset:49152
	ds_read_b128 v[186:189], v149 offset:50176
	ds_read_b128 v[190:193], v149 offset:51200
	ds_read_b128 v[194:197], v149 offset:52224
	ds_read_b128 v[198:201], v149 offset:53248
	ds_read_b128 v[202:205], v149 offset:54272
	ds_read_b128 v[206:209], v149 offset:55296
	ds_read_b128 v[224:227], v149 offset:56320
	global_load_lds_dwordx4 v[144:145], off
	s_add_i32 m0, s64, 0x2000
	s_add_u32 s64, s68, 0x20080
	v_lshl_add_u64 v[144:145], v[210:211], 0, s[48:49]
	s_addc_u32 s65, s69, 0
	s_add_i32 s68, s84, s63
	global_load_lds_dwordx4 v[144:145], off
	v_lshl_add_u64 v[144:145], s[64:65], 0, v[0:1]
	s_mov_b32 m0, s68
	s_nop 0
	global_load_lds_dwordx4 v[144:145], off
	v_lshl_add_u64 v[144:145], s[64:65], 0, v[134:135]
	s_add_i32 m0, s68, 0x2000
	s_nop 0
	global_load_lds_dwordx4 v[144:145], off
	v_lshl_add_u64 v[144:145], v[220:221], 0, s[48:49]
	s_mov_b32 m0, s74
	s_nop 0
	global_load_lds_dwordx4 v[144:145], off
	v_lshl_add_u64 v[144:145], v[228:229], 0, s[48:49]
	s_mov_b32 m0, s75
	s_nop 0
	global_load_lds_dwordx4 v[144:145], off
	s_waitcnt vmcnt(8)
	s_waitcnt lgkmcnt(0)
	s_barrier
	s_setprio 1
	s_waitcnt lgkmcnt(0)
	v_mfma_f32_16x16x32_bf16 v[62:65], v[150:153], v[182:185], v[62:65]
	v_mfma_f32_16x16x32_bf16 v[58:61], v[158:161], v[182:185], v[58:61]
	v_mfma_f32_16x16x32_bf16 v[54:57], v[150:153], v[190:193], v[54:57]
	v_mfma_f32_16x16x32_bf16 v[46:49], v[158:161], v[190:193], v[46:49]
	v_mfma_f32_16x16x32_bf16 v[38:41], v[150:153], v[198:201], v[38:41]
	v_mfma_f32_16x16x32_bf16 v[30:33], v[158:161], v[198:201], v[30:33]
	v_mfma_f32_16x16x32_bf16 v[22:25], v[150:153], v[206:209], v[22:25]
	v_mfma_f32_16x16x32_bf16 v[14:17], v[158:161], v[206:209], v[14:17]
	v_mfma_f32_16x16x32_bf16 v[62:65], v[154:157], v[186:189], v[62:65]
	v_mfma_f32_16x16x32_bf16 v[58:61], v[162:165], v[186:189], v[58:61]
	v_mfma_f32_16x16x32_bf16 v[54:57], v[154:157], v[194:197], v[54:57]
	v_mfma_f32_16x16x32_bf16 v[46:49], v[162:165], v[194:197], v[46:49]
	v_mfma_f32_16x16x32_bf16 v[38:41], v[154:157], v[202:205], v[38:41]
	v_mfma_f32_16x16x32_bf16 v[30:33], v[162:165], v[202:205], v[30:33]
	v_mfma_f32_16x16x32_bf16 v[22:25], v[154:157], v[224:227], v[22:25]
	v_mfma_f32_16x16x32_bf16 v[14:17], v[162:165], v[224:227], v[14:17]
	s_setprio 0
	s_setprio 1
	v_mfma_f32_16x16x32_bf16 v[50:53], v[166:169], v[182:185], v[50:53]
	v_mfma_f32_16x16x32_bf16 v[42:45], v[174:177], v[182:185], v[42:45]
	v_mfma_f32_16x16x32_bf16 v[34:37], v[166:169], v[190:193], v[34:37]
	v_mfma_f32_16x16x32_bf16 v[26:29], v[174:177], v[190:193], v[26:29]
	v_mfma_f32_16x16x32_bf16 v[18:21], v[166:169], v[198:201], v[18:21]
	v_mfma_f32_16x16x32_bf16 v[10:13], v[174:177], v[198:201], v[10:13]
	v_mfma_f32_16x16x32_bf16 v[6:9], v[166:169], v[206:209], v[6:9]
	v_mfma_f32_16x16x32_bf16 v[2:5], v[174:177], v[206:209], v[2:5]
	v_mfma_f32_16x16x32_bf16 v[50:53], v[170:173], v[186:189], v[50:53]
	v_mfma_f32_16x16x32_bf16 v[42:45], v[178:181], v[186:189], v[42:45]
	v_mfma_f32_16x16x32_bf16 v[34:37], v[170:173], v[194:197], v[34:37]
	v_mfma_f32_16x16x32_bf16 v[26:29], v[178:181], v[194:197], v[26:29]
	v_mfma_f32_16x16x32_bf16 v[18:21], v[170:173], v[202:205], v[18:21]
	v_mfma_f32_16x16x32_bf16 v[10:13], v[178:181], v[202:205], v[10:13]
	v_mfma_f32_16x16x32_bf16 v[6:9], v[170:173], v[224:227], v[6:9]
	v_mfma_f32_16x16x32_bf16 v[2:5], v[178:181], v[224:227], v[2:5]
	s_setprio 0
	s_barrier
	s_add_i32 s82, s82, 2
	s_add_u32 s6, s6, 0x100
	s_addc_u32 s7, s7, 0
	s_add_u32 s80, s80, 0x100
	s_addc_u32 s81, s81, 0

.LBB0_1602:
	s_ashr_i32 s13, s16, 3
	s_add_i32 s13, s16, s13
	s_and_b64 s[18:19], s[66:67], s[4:5]
	s_add_i32 s13, s13, 1
	s_and_b64 s[18:19], s[18:19], exec
	s_cselect_b32 s16, s13, s16
	s_ashr_i32 s17, s16, 31
	s_lshl_b64 s[18:19], s[16:17], 19
	s_add_u32 s18, s37, s18
	s_addc_u32 s19, s60, s19
	s_and_b64 s[20:21], s[4:5], exec
	s_cselect_b32 s17, s19, s57
	s_cselect_b32 s27, s18, s56
	s_ashr_i32 s13, s12, 31
	s_lshl_b64 s[20:21], s[12:13], 19
	s_add_u32 s20, s63, s20
	s_addc_u32 s21, s72, s21
	s_and_b64 s[30:31], s[4:5], exec
	s_cselect_b32 s13, s21, s69
	s_cselect_b32 s30, s20, s68
	s_add_u32 s56, s56, 0x40080
	s_addc_u32 s57, s57, 0
	s_add_u32 s31, s68, 0x100
	s_addc_u32 s85, s69, 0
	s_mov_b32 s86, -2
	s_add_u32 s64, s56, 0xfffc0080
	s_addc_u32 s65, s57, -1
	s_add_i32 s87, 0, 0x10000
	s_cmp_eq_u32 s86, 12
	s_cselect_b32 s71, s17, s65
	s_cselect_b32 s70, s27, s64
	v_add_u32_e32 v144, s87, v147
	s_cselect_b32 s69, s13, s85
	s_cselect_b32 s68, s30, s31
	s_add_i32 s88, 0, 0x14000
	ds_read_b128 v[140:143], v144
	ds_read_b128 v[150:153], v144 offset:1024
	ds_read_b128 v[154:157], v144 offset:2048
	ds_read_b128 v[158:161], v144 offset:3072
	v_add_u32_e32 v144, s88, v147
	ds_read_b128 v[162:165], v144
	ds_read_b128 v[166:169], v144 offset:1024
	ds_read_b128 v[170:173], v144 offset:2048
	ds_read_b128 v[174:177], v144 offset:3072
	v_lshl_add_u64 v[144:145], s[56:57], 0, v[136:137]
	s_add_i32 m0, s53, 0xc000
	ds_read_b128 v[178:181], v149
	ds_read_b128 v[182:185], v149 offset:1024
	ds_read_b128 v[186:189], v149 offset:2048
	ds_read_b128 v[190:193], v149 offset:3072
	ds_read_b128 v[194:197], v149 offset:4096
	ds_read_b128 v[198:201], v149 offset:5120
	ds_read_b128 v[202:205], v149 offset:6144
	ds_read_b128 v[206:209], v149 offset:7168
	global_load_lds_dwordx4 v[144:145], off
	v_lshl_add_u64 v[144:145], s[56:57], 0, v[138:139]
	s_add_i32 m0, s53, 0xe000
	s_nop 0
	global_load_lds_dwordx4 v[144:145], off
	s_waitcnt vmcnt(8)
	s_waitcnt lgkmcnt(0)
	s_barrier
	s_setprio 1
	s_waitcnt lgkmcnt(0)
	v_mfma_f32_16x16x32_bf16 v[126:129], v[140:143], v[178:181], 0
	v_mfma_f32_16x16x32_bf16 v[122:125], v[154:157], v[178:181], 0
	v_mfma_f32_16x16x32_bf16 v[110:113], v[140:143], v[186:189], 0
	v_mfma_f32_16x16x32_bf16 v[106:109], v[154:157], v[186:189], 0
	v_mfma_f32_16x16x32_bf16 v[94:97], v[140:143], v[194:197], 0
	v_mfma_f32_16x16x32_bf16 v[90:93], v[154:157], v[194:197], 0
	v_mfma_f32_16x16x32_bf16 v[78:81], v[140:143], v[202:205], 0
	v_mfma_f32_16x16x32_bf16 v[74:77], v[154:157], v[202:205], 0
	v_mfma_f32_16x16x32_bf16 v[126:129], v[150:153], v[182:185], v[126:129]
	v_mfma_f32_16x16x32_bf16 v[122:125], v[158:161], v[182:185], v[122:125]
	v_mfma_f32_16x16x32_bf16 v[110:113], v[150:153], v[190:193], v[110:113]
	v_mfma_f32_16x16x32_bf16 v[106:109], v[158:161], v[190:193], v[106:109]
	v_mfma_f32_16x16x32_bf16 v[94:97], v[150:153], v[198:201], v[94:97]
	v_mfma_f32_16x16x32_bf16 v[90:93], v[158:161], v[198:201], v[90:93]
	v_mfma_f32_16x16x32_bf16 v[78:81], v[150:153], v[206:209], v[78:81]
	v_mfma_f32_16x16x32_bf16 v[74:77], v[158:161], v[206:209], v[74:77]
	s_setprio 0
	s_setprio 1
	v_mfma_f32_16x16x32_bf16 v[118:121], v[162:165], v[178:181], 0
	v_mfma_f32_16x16x32_bf16 v[114:117], v[170:173], v[178:181], 0
	v_mfma_f32_16x16x32_bf16 v[102:105], v[162:165], v[186:189], 0
	v_mfma_f32_16x16x32_bf16 v[98:101], v[170:173], v[186:189], 0
	v_mfma_f32_16x16x32_bf16 v[86:89], v[162:165], v[194:197], 0
	v_mfma_f32_16x16x32_bf16 v[82:85], v[170:173], v[194:197], 0
	v_mfma_f32_16x16x32_bf16 v[70:73], v[162:165], v[202:205], 0
	v_mfma_f32_16x16x32_bf16 v[66:69], v[170:173], v[202:205], 0
	v_mfma_f32_16x16x32_bf16 v[118:121], v[166:169], v[182:185], v[118:121]
	v_mfma_f32_16x16x32_bf16 v[114:117], v[174:177], v[182:185], v[114:117]
	v_mfma_f32_16x16x32_bf16 v[102:105], v[166:169], v[190:193], v[102:105]
	v_mfma_f32_16x16x32_bf16 v[98:101], v[174:177], v[190:193], v[98:101]
	v_mfma_f32_16x16x32_bf16 v[86:89], v[166:169], v[198:201], v[86:89]
	v_mfma_f32_16x16x32_bf16 v[82:85], v[174:177], v[198:201], v[82:85]
	v_mfma_f32_16x16x32_bf16 v[70:73], v[166:169], v[206:209], v[70:73]
	v_mfma_f32_16x16x32_bf16 v[66:69], v[174:177], v[206:209], v[66:69]
	s_setprio 0
	s_barrier
	s_add_i32 s64, s87, s73
	v_lshl_add_u64 v[144:145], s[68:69], 0, v[0:1]
	s_mov_b32 m0, s64
	ds_read_b128 v[178:181], v149 offset:16384
	ds_read_b128 v[182:185], v149 offset:17408
	ds_read_b128 v[186:189], v149 offset:18432
	ds_read_b128 v[190:193], v149 offset:19456
	ds_read_b128 v[194:197], v149 offset:20480
	ds_read_b128 v[198:201], v149 offset:21504
	ds_read_b128 v[202:205], v149 offset:22528
	ds_read_b128 v[206:209], v149 offset:23552
	global_load_lds_dwordx4 v[144:145], off
	s_add_i32 m0, s64, 0x2000
	s_add_u32 s64, s68, 0x40000
	v_lshl_add_u64 v[210:211], s[68:69], 0, v[134:135]
	s_addc_u32 s65, s69, 0
	s_add_i32 s87, s88, s73
	global_load_lds_dwordx4 v[210:211], off
	v_lshl_add_u64 v[220:221], s[64:65], 0, v[0:1]
	s_mov_b32 m0, s87
	v_lshl_add_u64 v[224:225], s[70:71], 0, v[134:135]
	global_load_lds_dwordx4 v[220:221], off
	v_lshl_add_u64 v[220:221], s[64:65], 0, v[134:135]
	s_add_i32 m0, s87, 0x2000
	s_nop 0
	global_load_lds_dwordx4 v[220:221], off
	v_lshl_add_u64 v[220:221], s[70:71], 0, v[0:1]
	s_mov_b32 m0, s53
	s_nop 0
	global_load_lds_dwordx4 v[220:221], off
	s_mov_b32 m0, s78
	s_nop 0
	global_load_lds_dwordx4 v[224:225], off
	s_waitcnt vmcnt(8)
	s_waitcnt lgkmcnt(0)
	s_barrier
	s_setprio 1
	s_waitcnt lgkmcnt(0)
	v_mfma_f32_16x16x32_bf16 v[62:65], v[140:143], v[178:181], 0
	v_mfma_f32_16x16x32_bf16 v[58:61], v[154:157], v[178:181], 0
	v_mfma_f32_16x16x32_bf16 v[46:49], v[140:143], v[186:189], 0
	v_mfma_f32_16x16x32_bf16 v[42:45], v[154:157], v[186:189], 0
	v_mfma_f32_16x16x32_bf16 v[30:33], v[140:143], v[194:197], 0
	v_mfma_f32_16x16x32_bf16 v[26:29], v[154:157], v[194:197], 0
	v_mfma_f32_16x16x32_bf16 v[14:17], v[140:143], v[202:205], 0
	v_mfma_f32_16x16x32_bf16 v[10:13], v[154:157], v[202:205], 0
	v_mfma_f32_16x16x32_bf16 v[62:65], v[150:153], v[182:185], v[62:65]
	v_mfma_f32_16x16x32_bf16 v[58:61], v[158:161], v[182:185], v[58:61]
	v_mfma_f32_16x16x32_bf16 v[46:49], v[150:153], v[190:193], v[46:49]
	v_mfma_f32_16x16x32_bf16 v[42:45], v[158:161], v[190:193], v[42:45]
	v_mfma_f32_16x16x32_bf16 v[30:33], v[150:153], v[198:201], v[30:33]
	v_mfma_f32_16x16x32_bf16 v[26:29], v[158:161], v[198:201], v[26:29]
	v_mfma_f32_16x16x32_bf16 v[14:17], v[150:153], v[206:209], v[14:17]
	v_mfma_f32_16x16x32_bf16 v[10:13], v[158:161], v[206:209], v[10:13]
	s_setprio 0
	s_setprio 1
	v_mfma_f32_16x16x32_bf16 v[54:57], v[162:165], v[178:181], 0
	v_mfma_f32_16x16x32_bf16 v[50:53], v[170:173], v[178:181], 0
	v_mfma_f32_16x16x32_bf16 v[38:41], v[162:165], v[186:189], 0
	v_mfma_f32_16x16x32_bf16 v[34:37], v[170:173], v[186:189], 0
	v_mfma_f32_16x16x32_bf16 v[22:25], v[162:165], v[194:197], 0
	v_mfma_f32_16x16x32_bf16 v[18:21], v[170:173], v[194:197], 0
	v_mfma_f32_16x16x32_bf16 v[6:9], v[162:165], v[202:205], 0
	v_mfma_f32_16x16x32_bf16 v[2:5], v[170:173], v[202:205], 0
	v_mfma_f32_16x16x32_bf16 v[54:57], v[166:169], v[182:185], v[54:57]
	v_mfma_f32_16x16x32_bf16 v[50:53], v[174:177], v[182:185], v[50:53]
	v_mfma_f32_16x16x32_bf16 v[38:41], v[166:169], v[190:193], v[38:41]
	v_mfma_f32_16x16x32_bf16 v[34:37], v[174:177], v[190:193], v[34:37]
	v_mfma_f32_16x16x32_bf16 v[22:25], v[166:169], v[198:201], v[22:25]
	v_mfma_f32_16x16x32_bf16 v[18:21], v[174:177], v[198:201], v[18:21]
	v_mfma_f32_16x16x32_bf16 v[6:9], v[166:169], v[206:209], v[6:9]
	v_mfma_f32_16x16x32_bf16 v[2:5], v[174:177], v[206:209], v[2:5]
	s_setprio 0
	s_barrier
	s_add_i32 s87, 0, 0x18000
	s_add_i32 s88, 0, 0x1c000
	v_add_u32_e32 v158, s87, v147
	v_add_u32_e32 v174, s88, v147
	ds_read_b128 v[140:143], v158
	ds_read_b128 v[150:153], v158 offset:1024
	ds_read_b128 v[154:157], v158 offset:2048
	ds_read_b128 v[158:161], v158 offset:3072
	ds_read_b128 v[162:165], v174
	ds_read_b128 v[166:169], v174 offset:1024
	ds_read_b128 v[170:173], v174 offset:2048
	ds_read_b128 v[174:177], v174 offset:3072
	s_add_u32 s64, s70, 0x40000
	s_addc_u32 s65, s71, 0
	s_mov_b32 m0, s79
	v_lshl_add_u64 v[226:227], s[64:65], 0, v[0:1]
	ds_read_b128 v[178:181], v149 offset:32768
	ds_read_b128 v[182:185], v149 offset:33792
	ds_read_b128 v[186:189], v149 offset:34816
	ds_read_b128 v[190:193], v149 offset:35840
	ds_read_b128 v[194:197], v149 offset:36864
	ds_read_b128 v[198:201], v149 offset:37888
	ds_read_b128 v[202:205], v149 offset:38912
	ds_read_b128 v[206:209], v149 offset:39936
	global_load_lds_dwordx4 v[226:227], off
	v_lshl_add_u64 v[226:227], s[64:65], 0, v[134:135]
	s_mov_b32 m0, s80
	s_nop 0
	global_load_lds_dwordx4 v[226:227], off
	s_waitcnt vmcnt(8)
	s_waitcnt lgkmcnt(0)
	s_barrier
	s_setprio 1
	s_waitcnt lgkmcnt(0)
	v_mfma_f32_16x16x32_bf16 v[126:129], v[140:143], v[178:181], v[126:129]
	v_mfma_f32_16x16x32_bf16 v[122:125], v[154:157], v[178:181], v[122:125]
	v_mfma_f32_16x16x32_bf16 v[110:113], v[140:143], v[186:189], v[110:113]
	v_mfma_f32_16x16x32_bf16 v[106:109], v[154:157], v[186:189], v[106:109]
	v_mfma_f32_16x16x32_bf16 v[94:97], v[140:143], v[194:197], v[94:97]
	v_mfma_f32_16x16x32_bf16 v[90:93], v[154:157], v[194:197], v[90:93]
	v_mfma_f32_16x16x32_bf16 v[78:81], v[140:143], v[202:205], v[78:81]
	v_mfma_f32_16x16x32_bf16 v[74:77], v[154:157], v[202:205], v[74:77]
	v_mfma_f32_16x16x32_bf16 v[126:129], v[150:153], v[182:185], v[126:129]
	v_mfma_f32_16x16x32_bf16 v[122:125], v[158:161], v[182:185], v[122:125]
	v_mfma_f32_16x16x32_bf16 v[110:113], v[150:153], v[190:193], v[110:113]
	v_mfma_f32_16x16x32_bf16 v[106:109], v[158:161], v[190:193], v[106:109]
	v_mfma_f32_16x16x32_bf16 v[94:97], v[150:153], v[198:201], v[94:97]
	v_mfma_f32_16x16x32_bf16 v[90:93], v[158:161], v[198:201], v[90:93]
	v_mfma_f32_16x16x32_bf16 v[78:81], v[150:153], v[206:209], v[78:81]
	v_mfma_f32_16x16x32_bf16 v[74:77], v[158:161], v[206:209], v[74:77]
	s_setprio 0
	s_setprio 1
	v_mfma_f32_16x16x32_bf16 v[118:121], v[162:165], v[178:181], v[118:121]
	v_mfma_f32_16x16x32_bf16 v[114:117], v[170:173], v[178:181], v[114:117]
	v_mfma_f32_16x16x32_bf16 v[102:105], v[162:165], v[186:189], v[102:105]
	v_mfma_f32_16x16x32_bf16 v[98:101], v[170:173], v[186:189], v[98:101]
	v_mfma_f32_16x16x32_bf16 v[86:89], v[162:165], v[194:197], v[86:89]
	v_mfma_f32_16x16x32_bf16 v[82:85], v[170:173], v[194:197], v[82:85]
	v_mfma_f32_16x16x32_bf16 v[70:73], v[162:165], v[202:205], v[70:73]
	v_mfma_f32_16x16x32_bf16 v[66:69], v[170:173], v[202:205], v[66:69]
	v_mfma_f32_16x16x32_bf16 v[118:121], v[166:169], v[182:185], v[118:121]
	v_mfma_f32_16x16x32_bf16 v[114:117], v[174:177], v[182:185], v[114:117]
	v_mfma_f32_16x16x32_bf16 v[102:105], v[166:169], v[190:193], v[102:105]
	v_mfma_f32_16x16x32_bf16 v[98:101], v[174:177], v[190:193], v[98:101]
	v_mfma_f32_16x16x32_bf16 v[86:89], v[166:169], v[198:201], v[86:89]
	v_mfma_f32_16x16x32_bf16 v[82:85], v[174:177], v[198:201], v[82:85]
	v_mfma_f32_16x16x32_bf16 v[70:73], v[166:169], v[206:209], v[70:73]
	v_mfma_f32_16x16x32_bf16 v[66:69], v[174:177], v[206:209], v[66:69]
	s_setprio 0
	s_barrier
	s_add_i32 s64, s87, s73
	v_lshl_add_u64 v[144:145], v[144:145], 0, s[48:49]
	s_mov_b32 m0, s64
	ds_read_b128 v[178:181], v149 offset:49152
	ds_read_b128 v[182:185], v149 offset:50176
	ds_read_b128 v[186:189], v149 offset:51200
	ds_read_b128 v[190:193], v149 offset:52224
	ds_read_b128 v[194:197], v149 offset:53248
	ds_read_b128 v[198:201], v149 offset:54272
	ds_read_b128 v[202:205], v149 offset:55296
	ds_read_b128 v[206:209], v149 offset:56320
	global_load_lds_dwordx4 v[144:145], off
	s_add_i32 m0, s64, 0x2000
	s_add_u32 s64, s68, 0x40080
	v_lshl_add_u64 v[144:145], v[210:211], 0, s[48:49]
	s_addc_u32 s65, s69, 0
	s_add_i32 s68, s88, s73
	global_load_lds_dwordx4 v[144:145], off
	v_lshl_add_u64 v[144:145], s[64:65], 0, v[0:1]
	s_mov_b32 m0, s68
	s_nop 0
	global_load_lds_dwordx4 v[144:145], off
	v_lshl_add_u64 v[144:145], s[64:65], 0, v[134:135]
	s_add_i32 m0, s68, 0x2000
	s_nop 0
	global_load_lds_dwordx4 v[144:145], off
	v_lshl_add_u64 v[144:145], v[220:221], 0, s[48:49]
	s_mov_b32 m0, s81
	s_nop 0
	global_load_lds_dwordx4 v[144:145], off
	v_lshl_add_u64 v[144:145], v[224:225], 0, s[48:49]
	s_mov_b32 m0, s82
	s_nop 0
	global_load_lds_dwordx4 v[144:145], off
	s_waitcnt vmcnt(8)
	s_waitcnt lgkmcnt(0)
	s_barrier
	s_setprio 1
	s_waitcnt lgkmcnt(0)
	v_mfma_f32_16x16x32_bf16 v[62:65], v[140:143], v[178:181], v[62:65]
	v_mfma_f32_16x16x32_bf16 v[58:61], v[154:157], v[178:181], v[58:61]
	v_mfma_f32_16x16x32_bf16 v[46:49], v[140:143], v[186:189], v[46:49]
	v_mfma_f32_16x16x32_bf16 v[42:45], v[154:157], v[186:189], v[42:45]
	v_mfma_f32_16x16x32_bf16 v[30:33], v[140:143], v[194:197], v[30:33]
	v_mfma_f32_16x16x32_bf16 v[26:29], v[154:157], v[194:197], v[26:29]
	v_mfma_f32_16x16x32_bf16 v[14:17], v[140:143], v[202:205], v[14:17]
	v_mfma_f32_16x16x32_bf16 v[10:13], v[154:157], v[202:205], v[10:13]
	v_mfma_f32_16x16x32_bf16 v[62:65], v[150:153], v[182:185], v[62:65]
	v_mfma_f32_16x16x32_bf16 v[58:61], v[158:161], v[182:185], v[58:61]
	v_mfma_f32_16x16x32_bf16 v[46:49], v[150:153], v[190:193], v[46:49]
	v_mfma_f32_16x16x32_bf16 v[42:45], v[158:161], v[190:193], v[42:45]
	v_mfma_f32_16x16x32_bf16 v[30:33], v[150:153], v[198:201], v[30:33]
	v_mfma_f32_16x16x32_bf16 v[26:29], v[158:161], v[198:201], v[26:29]
	v_mfma_f32_16x16x32_bf16 v[14:17], v[150:153], v[206:209], v[14:17]
	v_mfma_f32_16x16x32_bf16 v[10:13], v[158:161], v[206:209], v[10:13]
	s_setprio 0
	s_setprio 1
	v_mfma_f32_16x16x32_bf16 v[54:57], v[162:165], v[178:181], v[54:57]
	v_mfma_f32_16x16x32_bf16 v[50:53], v[170:173], v[178:181], v[50:53]
	v_mfma_f32_16x16x32_bf16 v[38:41], v[162:165], v[186:189], v[38:41]
	v_mfma_f32_16x16x32_bf16 v[34:37], v[170:173], v[186:189], v[34:37]
	v_mfma_f32_16x16x32_bf16 v[22:25], v[162:165], v[194:197], v[22:25]
	v_mfma_f32_16x16x32_bf16 v[18:21], v[170:173], v[194:197], v[18:21]
	v_mfma_f32_16x16x32_bf16 v[6:9], v[162:165], v[202:205], v[6:9]
	v_mfma_f32_16x16x32_bf16 v[2:5], v[170:173], v[202:205], v[2:5]
	v_mfma_f32_16x16x32_bf16 v[54:57], v[166:169], v[182:185], v[54:57]
	v_mfma_f32_16x16x32_bf16 v[50:53], v[174:177], v[182:185], v[50:53]
	v_mfma_f32_16x16x32_bf16 v[38:41], v[166:169], v[190:193], v[38:41]
	v_mfma_f32_16x16x32_bf16 v[34:37], v[174:177], v[190:193], v[34:37]
	v_mfma_f32_16x16x32_bf16 v[22:25], v[166:169], v[198:201], v[22:25]
	v_mfma_f32_16x16x32_bf16 v[18:21], v[174:177], v[198:201], v[18:21]
	v_mfma_f32_16x16x32_bf16 v[6:9], v[166:169], v[206:209], v[6:9]
	v_mfma_f32_16x16x32_bf16 v[2:5], v[174:177], v[206:209], v[2:5]
	s_setprio 0
	s_barrier
	s_add_i32 s86, s86, 2
	s_add_u32 s56, s56, 0x100
	s_addc_u32 s57, s57, 0
	s_add_u32 s31, s31, 0x100
	s_addc_u32 s85, s85, 0

.LBB0_1670:
	s_ashr_i32 s11, s12, 3
	s_add_i32 s11, s12, s11
	s_and_b64 s[16:17], s[66:67], s[4:5]
	s_add_i32 s11, s11, 1
	s_and_b64 s[16:17], s[16:17], exec
	s_cselect_b32 s12, s11, s12
	s_ashr_i32 s13, s12, 31
	s_lshl_b64 s[16:17], s[12:13], 19
	s_add_u32 s16, s31, s16
	s_addc_u32 s17, s36, s17
	s_and_b64 s[26:27], s[4:5], exec
	s_cselect_b32 s13, s17, s53
	s_cselect_b32 s79, s16, s52
	s_ashr_i32 s11, s10, 31
	s_lshl_b64 s[26:27], s[10:11], 19
	s_add_u32 s26, s37, s26
	s_addc_u32 s27, s60, s27
	s_and_b64 s[64:65], s[4:5], exec
	s_cselect_b32 s11, s27, s57
	s_cselect_b32 s80, s26, s56
	s_add_u32 s52, s52, 0x40080
	s_addc_u32 s53, s53, 0
	s_add_u32 s81, s56, 0x100
	s_addc_u32 s82, s57, 0
	s_mov_b32 s83, -2
	s_add_u32 s56, s52, 0xfffc0080
	s_addc_u32 s57, s53, -1
	s_add_i32 s64, 0, 0x10000
	s_cmp_eq_u32 s83, 12
	s_cselect_b32 s69, s13, s57
	s_cselect_b32 s68, s79, s56
	v_add_u32_e32 v144, s64, v147
	s_cselect_b32 s57, s11, s82
	s_cselect_b32 s56, s80, s81
	s_add_i32 s84, 0, 0x14000
	ds_read_b128 v[150:153], v144
	ds_read_b128 v[154:157], v144 offset:1024
	ds_read_b128 v[158:161], v144 offset:2048
	ds_read_b128 v[162:165], v144 offset:3072
	v_add_u32_e32 v144, s84, v147
	ds_read_b128 v[166:169], v144
	ds_read_b128 v[170:173], v144 offset:1024
	ds_read_b128 v[174:177], v144 offset:2048
	ds_read_b128 v[178:181], v144 offset:3072
	v_lshl_add_u64 v[144:145], s[52:53], 0, v[140:141]
	s_add_i32 m0, s19, 0xc000
	ds_read_b128 v[182:185], v149
	ds_read_b128 v[186:189], v149 offset:1024
	ds_read_b128 v[190:193], v149 offset:2048
	ds_read_b128 v[194:197], v149 offset:3072
	ds_read_b128 v[198:201], v149 offset:4096
	ds_read_b128 v[202:205], v149 offset:5120
	ds_read_b128 v[206:209], v149 offset:6144
	ds_read_b128 v[224:227], v149 offset:7168
	global_load_lds_dwordx4 v[144:145], off
	v_lshl_add_u64 v[144:145], s[52:53], 0, v[142:143]
	s_add_i32 m0, s19, 0xe000
	s_nop 0
	global_load_lds_dwordx4 v[144:145], off
	s_waitcnt vmcnt(8)
	s_waitcnt lgkmcnt(0)
	s_barrier
	s_setprio 1
	s_waitcnt lgkmcnt(0)
	v_mfma_f32_16x16x32_bf16 v[126:129], v[150:153], v[182:185], 0
	v_mfma_f32_16x16x32_bf16 v[122:125], v[158:161], v[182:185], 0
	v_mfma_f32_16x16x32_bf16 v[118:121], v[150:153], v[190:193], 0
	v_mfma_f32_16x16x32_bf16 v[110:113], v[158:161], v[190:193], 0
	v_mfma_f32_16x16x32_bf16 v[102:105], v[150:153], v[198:201], 0
	v_mfma_f32_16x16x32_bf16 v[94:97], v[158:161], v[198:201], 0
	v_mfma_f32_16x16x32_bf16 v[86:89], v[150:153], v[206:209], 0
	v_mfma_f32_16x16x32_bf16 v[78:81], v[158:161], v[206:209], 0
	v_mfma_f32_16x16x32_bf16 v[126:129], v[154:157], v[186:189], v[126:129]
	v_mfma_f32_16x16x32_bf16 v[122:125], v[162:165], v[186:189], v[122:125]
	v_mfma_f32_16x16x32_bf16 v[118:121], v[154:157], v[194:197], v[118:121]
	v_mfma_f32_16x16x32_bf16 v[110:113], v[162:165], v[194:197], v[110:113]
	v_mfma_f32_16x16x32_bf16 v[102:105], v[154:157], v[202:205], v[102:105]
	v_mfma_f32_16x16x32_bf16 v[94:97], v[162:165], v[202:205], v[94:97]
	v_mfma_f32_16x16x32_bf16 v[86:89], v[154:157], v[224:227], v[86:89]
	v_mfma_f32_16x16x32_bf16 v[78:81], v[162:165], v[224:227], v[78:81]
	s_setprio 0
	s_setprio 1
	v_mfma_f32_16x16x32_bf16 v[114:117], v[166:169], v[182:185], 0
	v_mfma_f32_16x16x32_bf16 v[106:109], v[174:177], v[182:185], 0
	v_mfma_f32_16x16x32_bf16 v[98:101], v[166:169], v[190:193], 0
	v_mfma_f32_16x16x32_bf16 v[90:93], v[174:177], v[190:193], 0
	v_mfma_f32_16x16x32_bf16 v[82:85], v[166:169], v[198:201], 0
	v_mfma_f32_16x16x32_bf16 v[74:77], v[174:177], v[198:201], 0
	v_mfma_f32_16x16x32_bf16 v[70:73], v[166:169], v[206:209], 0
	v_mfma_f32_16x16x32_bf16 v[66:69], v[174:177], v[206:209], 0
	v_mfma_f32_16x16x32_bf16 v[114:117], v[170:173], v[186:189], v[114:117]
	v_mfma_f32_16x16x32_bf16 v[106:109], v[178:181], v[186:189], v[106:109]
	v_mfma_f32_16x16x32_bf16 v[98:101], v[170:173], v[194:197], v[98:101]
	v_mfma_f32_16x16x32_bf16 v[90:93], v[178:181], v[194:197], v[90:93]
	v_mfma_f32_16x16x32_bf16 v[82:85], v[170:173], v[202:205], v[82:85]
	v_mfma_f32_16x16x32_bf16 v[74:77], v[178:181], v[202:205], v[74:77]
	v_mfma_f32_16x16x32_bf16 v[70:73], v[170:173], v[224:227], v[70:73]
	v_mfma_f32_16x16x32_bf16 v[66:69], v[178:181], v[224:227], v[66:69]
	s_setprio 0
	s_barrier
	s_add_i32 s64, s64, s63
	v_lshl_add_u64 v[144:145], s[56:57], 0, v[0:1]
	s_mov_b32 m0, s64
	ds_read_b128 v[182:185], v149 offset:16384
	ds_read_b128 v[186:189], v149 offset:17408
	ds_read_b128 v[190:193], v149 offset:18432
	ds_read_b128 v[194:197], v149 offset:19456
	ds_read_b128 v[198:201], v149 offset:20480
	ds_read_b128 v[202:205], v149 offset:21504
	ds_read_b128 v[206:209], v149 offset:22528
	ds_read_b128 v[224:227], v149 offset:23552
	global_load_lds_dwordx4 v[144:145], off
	s_add_i32 m0, s64, 0x2000
	s_add_u32 s64, s56, 0x40000
	v_lshl_add_u64 v[210:211], s[56:57], 0, v[134:135]
	s_addc_u32 s65, s57, 0
	s_add_i32 s84, s84, s63
	global_load_lds_dwordx4 v[210:211], off
	v_lshl_add_u64 v[220:221], s[64:65], 0, v[0:1]
	s_mov_b32 m0, s84
	v_lshl_add_u64 v[228:229], s[68:69], 0, v[136:137]
	global_load_lds_dwordx4 v[220:221], off
	v_lshl_add_u64 v[220:221], s[64:65], 0, v[134:135]
	s_add_i32 m0, s84, 0x2000
	s_nop 0
	global_load_lds_dwordx4 v[220:221], off
	v_lshl_add_u64 v[220:221], s[68:69], 0, v[138:139]
	s_mov_b32 m0, s19
	s_nop 0
	global_load_lds_dwordx4 v[220:221], off
	s_mov_b32 m0, s21
	s_nop 0
	global_load_lds_dwordx4 v[228:229], off
	s_waitcnt vmcnt(8)
	s_waitcnt lgkmcnt(0)
	s_barrier
	s_setprio 1
	s_waitcnt lgkmcnt(0)
	v_mfma_f32_16x16x32_bf16 v[62:65], v[150:153], v[182:185], 0
	v_mfma_f32_16x16x32_bf16 v[58:61], v[158:161], v[182:185], 0
	v_mfma_f32_16x16x32_bf16 v[54:57], v[150:153], v[190:193], 0
	v_mfma_f32_16x16x32_bf16 v[46:49], v[158:161], v[190:193], 0
	v_mfma_f32_16x16x32_bf16 v[38:41], v[150:153], v[198:201], 0
	v_mfma_f32_16x16x32_bf16 v[30:33], v[158:161], v[198:201], 0
	v_mfma_f32_16x16x32_bf16 v[22:25], v[150:153], v[206:209], 0
	v_mfma_f32_16x16x32_bf16 v[14:17], v[158:161], v[206:209], 0
	v_mfma_f32_16x16x32_bf16 v[62:65], v[154:157], v[186:189], v[62:65]
	v_mfma_f32_16x16x32_bf16 v[58:61], v[162:165], v[186:189], v[58:61]
	v_mfma_f32_16x16x32_bf16 v[54:57], v[154:157], v[194:197], v[54:57]
	v_mfma_f32_16x16x32_bf16 v[46:49], v[162:165], v[194:197], v[46:49]
	v_mfma_f32_16x16x32_bf16 v[38:41], v[154:157], v[202:205], v[38:41]
	v_mfma_f32_16x16x32_bf16 v[30:33], v[162:165], v[202:205], v[30:33]
	v_mfma_f32_16x16x32_bf16 v[22:25], v[154:157], v[224:227], v[22:25]
	v_mfma_f32_16x16x32_bf16 v[14:17], v[162:165], v[224:227], v[14:17]
	s_setprio 0
	s_setprio 1
	v_mfma_f32_16x16x32_bf16 v[50:53], v[166:169], v[182:185], 0
	v_mfma_f32_16x16x32_bf16 v[42:45], v[174:177], v[182:185], 0
	v_mfma_f32_16x16x32_bf16 v[34:37], v[166:169], v[190:193], 0
	v_mfma_f32_16x16x32_bf16 v[26:29], v[174:177], v[190:193], 0
	v_mfma_f32_16x16x32_bf16 v[18:21], v[166:169], v[198:201], 0
	v_mfma_f32_16x16x32_bf16 v[10:13], v[174:177], v[198:201], 0
	v_mfma_f32_16x16x32_bf16 v[6:9], v[166:169], v[206:209], 0
	v_mfma_f32_16x16x32_bf16 v[2:5], v[174:177], v[206:209], 0
	v_mfma_f32_16x16x32_bf16 v[50:53], v[170:173], v[186:189], v[50:53]
	v_mfma_f32_16x16x32_bf16 v[42:45], v[178:181], v[186:189], v[42:45]
	v_mfma_f32_16x16x32_bf16 v[34:37], v[170:173], v[194:197], v[34:37]
	v_mfma_f32_16x16x32_bf16 v[26:29], v[178:181], v[194:197], v[26:29]
	v_mfma_f32_16x16x32_bf16 v[18:21], v[170:173], v[202:205], v[18:21]
	v_mfma_f32_16x16x32_bf16 v[10:13], v[178:181], v[202:205], v[10:13]
	v_mfma_f32_16x16x32_bf16 v[6:9], v[170:173], v[224:227], v[6:9]
	v_mfma_f32_16x16x32_bf16 v[2:5], v[178:181], v[224:227], v[2:5]
	s_setprio 0
	s_barrier
	s_add_i32 s84, 0, 0x18000
	s_add_i32 s85, 0, 0x1c000
	v_add_u32_e32 v162, s84, v147
	v_add_u32_e32 v178, s85, v147
	ds_read_b128 v[150:153], v162
	ds_read_b128 v[154:157], v162 offset:1024
	ds_read_b128 v[158:161], v162 offset:2048
	ds_read_b128 v[162:165], v162 offset:3072
	ds_read_b128 v[166:169], v178
	ds_read_b128 v[170:173], v178 offset:1024
	ds_read_b128 v[174:177], v178 offset:2048
	ds_read_b128 v[178:181], v178 offset:3072
	s_add_u32 s64, s68, 0x40000
	s_addc_u32 s65, s69, 0
	s_mov_b32 m0, s71
	v_lshl_add_u64 v[230:231], s[64:65], 0, v[138:139]
	ds_read_b128 v[182:185], v149 offset:32768
	ds_read_b128 v[186:189], v149 offset:33792
	ds_read_b128 v[190:193], v149 offset:34816
	ds_read_b128 v[194:197], v149 offset:35840
	ds_read_b128 v[198:201], v149 offset:36864
	ds_read_b128 v[202:205], v149 offset:37888
	ds_read_b128 v[206:209], v149 offset:38912
	ds_read_b128 v[224:227], v149 offset:39936
	global_load_lds_dwordx4 v[230:231], off
	v_lshl_add_u64 v[230:231], s[64:65], 0, v[136:137]
	s_mov_b32 m0, s72
	s_nop 0
	global_load_lds_dwordx4 v[230:231], off
	s_waitcnt vmcnt(8)
	s_waitcnt lgkmcnt(0)
	s_barrier
	s_setprio 1
	s_waitcnt lgkmcnt(0)
	v_mfma_f32_16x16x32_bf16 v[126:129], v[150:153], v[182:185], v[126:129]
	v_mfma_f32_16x16x32_bf16 v[122:125], v[158:161], v[182:185], v[122:125]
	v_mfma_f32_16x16x32_bf16 v[118:121], v[150:153], v[190:193], v[118:121]
	v_mfma_f32_16x16x32_bf16 v[110:113], v[158:161], v[190:193], v[110:113]
	v_mfma_f32_16x16x32_bf16 v[102:105], v[150:153], v[198:201], v[102:105]
	v_mfma_f32_16x16x32_bf16 v[94:97], v[158:161], v[198:201], v[94:97]
	v_mfma_f32_16x16x32_bf16 v[86:89], v[150:153], v[206:209], v[86:89]
	v_mfma_f32_16x16x32_bf16 v[78:81], v[158:161], v[206:209], v[78:81]
	v_mfma_f32_16x16x32_bf16 v[126:129], v[154:157], v[186:189], v[126:129]
	v_mfma_f32_16x16x32_bf16 v[122:125], v[162:165], v[186:189], v[122:125]
	v_mfma_f32_16x16x32_bf16 v[118:121], v[154:157], v[194:197], v[118:121]
	v_mfma_f32_16x16x32_bf16 v[110:113], v[162:165], v[194:197], v[110:113]
	v_mfma_f32_16x16x32_bf16 v[102:105], v[154:157], v[202:205], v[102:105]
	v_mfma_f32_16x16x32_bf16 v[94:97], v[162:165], v[202:205], v[94:97]
	v_mfma_f32_16x16x32_bf16 v[86:89], v[154:157], v[224:227], v[86:89]
	v_mfma_f32_16x16x32_bf16 v[78:81], v[162:165], v[224:227], v[78:81]
	s_setprio 0
	s_setprio 1
	v_mfma_f32_16x16x32_bf16 v[114:117], v[166:169], v[182:185], v[114:117]
	v_mfma_f32_16x16x32_bf16 v[106:109], v[174:177], v[182:185], v[106:109]
	v_mfma_f32_16x16x32_bf16 v[98:101], v[166:169], v[190:193], v[98:101]
	v_mfma_f32_16x16x32_bf16 v[90:93], v[174:177], v[190:193], v[90:93]
	v_mfma_f32_16x16x32_bf16 v[82:85], v[166:169], v[198:201], v[82:85]
	v_mfma_f32_16x16x32_bf16 v[74:77], v[174:177], v[198:201], v[74:77]
	v_mfma_f32_16x16x32_bf16 v[70:73], v[166:169], v[206:209], v[70:73]
	v_mfma_f32_16x16x32_bf16 v[66:69], v[174:177], v[206:209], v[66:69]
	v_mfma_f32_16x16x32_bf16 v[114:117], v[170:173], v[186:189], v[114:117]
	v_mfma_f32_16x16x32_bf16 v[106:109], v[178:181], v[186:189], v[106:109]
	v_mfma_f32_16x16x32_bf16 v[98:101], v[170:173], v[194:197], v[98:101]
	v_mfma_f32_16x16x32_bf16 v[90:93], v[178:181], v[194:197], v[90:93]
	v_mfma_f32_16x16x32_bf16 v[82:85], v[170:173], v[202:205], v[82:85]
	v_mfma_f32_16x16x32_bf16 v[74:77], v[178:181], v[202:205], v[74:77]
	v_mfma_f32_16x16x32_bf16 v[70:73], v[170:173], v[224:227], v[70:73]
	v_mfma_f32_16x16x32_bf16 v[66:69], v[178:181], v[224:227], v[66:69]
	s_setprio 0
	s_barrier
	s_add_i32 s64, s84, s63
	v_lshl_add_u64 v[144:145], v[144:145], 0, s[48:49]
	s_mov_b32 m0, s64
	ds_read_b128 v[182:185], v149 offset:49152
	ds_read_b128 v[186:189], v149 offset:50176
	ds_read_b128 v[190:193], v149 offset:51200
	ds_read_b128 v[194:197], v149 offset:52224
	ds_read_b128 v[198:201], v149 offset:53248
	ds_read_b128 v[202:205], v149 offset:54272
	ds_read_b128 v[206:209], v149 offset:55296
	ds_read_b128 v[224:227], v149 offset:56320
	global_load_lds_dwordx4 v[144:145], off
	s_add_i32 m0, s64, 0x2000
	s_add_u32 s56, s56, 0x40080
	v_lshl_add_u64 v[144:145], v[210:211], 0, s[48:49]
	s_addc_u32 s57, s57, 0
	s_add_i32 s64, s85, s63
	global_load_lds_dwordx4 v[144:145], off
	v_lshl_add_u64 v[144:145], s[56:57], 0, v[0:1]
	s_mov_b32 m0, s64
	s_nop 0
	global_load_lds_dwordx4 v[144:145], off
	v_lshl_add_u64 v[144:145], s[56:57], 0, v[134:135]
	s_add_i32 m0, s64, 0x2000
	s_nop 0
	global_load_lds_dwordx4 v[144:145], off
	v_lshl_add_u64 v[144:145], v[220:221], 0, s[48:49]
	s_mov_b32 m0, s73
	s_nop 0
	global_load_lds_dwordx4 v[144:145], off
	v_lshl_add_u64 v[144:145], v[228:229], 0, s[48:49]
	s_mov_b32 m0, s74
	s_nop 0
	global_load_lds_dwordx4 v[144:145], off
	s_waitcnt vmcnt(8)
	s_waitcnt lgkmcnt(0)
	s_barrier
	s_setprio 1
	s_waitcnt lgkmcnt(0)
	v_mfma_f32_16x16x32_bf16 v[62:65], v[150:153], v[182:185], v[62:65]
	v_mfma_f32_16x16x32_bf16 v[58:61], v[158:161], v[182:185], v[58:61]
	v_mfma_f32_16x16x32_bf16 v[54:57], v[150:153], v[190:193], v[54:57]
	v_mfma_f32_16x16x32_bf16 v[46:49], v[158:161], v[190:193], v[46:49]
	v_mfma_f32_16x16x32_bf16 v[38:41], v[150:153], v[198:201], v[38:41]
	v_mfma_f32_16x16x32_bf16 v[30:33], v[158:161], v[198:201], v[30:33]
	v_mfma_f32_16x16x32_bf16 v[22:25], v[150:153], v[206:209], v[22:25]
	v_mfma_f32_16x16x32_bf16 v[14:17], v[158:161], v[206:209], v[14:17]
	v_mfma_f32_16x16x32_bf16 v[62:65], v[154:157], v[186:189], v[62:65]
	v_mfma_f32_16x16x32_bf16 v[58:61], v[162:165], v[186:189], v[58:61]
	v_mfma_f32_16x16x32_bf16 v[54:57], v[154:157], v[194:197], v[54:57]
	v_mfma_f32_16x16x32_bf16 v[46:49], v[162:165], v[194:197], v[46:49]
	v_mfma_f32_16x16x32_bf16 v[38:41], v[154:157], v[202:205], v[38:41]
	v_mfma_f32_16x16x32_bf16 v[30:33], v[162:165], v[202:205], v[30:33]
	v_mfma_f32_16x16x32_bf16 v[22:25], v[154:157], v[224:227], v[22:25]
	v_mfma_f32_16x16x32_bf16 v[14:17], v[162:165], v[224:227], v[14:17]
	s_setprio 0
	s_setprio 1
	v_mfma_f32_16x16x32_bf16 v[50:53], v[166:169], v[182:185], v[50:53]
	v_mfma_f32_16x16x32_bf16 v[42:45], v[174:177], v[182:185], v[42:45]
	v_mfma_f32_16x16x32_bf16 v[34:37], v[166:169], v[190:193], v[34:37]
	v_mfma_f32_16x16x32_bf16 v[26:29], v[174:177], v[190:193], v[26:29]
	v_mfma_f32_16x16x32_bf16 v[18:21], v[166:169], v[198:201], v[18:21]
	v_mfma_f32_16x16x32_bf16 v[10:13], v[174:177], v[198:201], v[10:13]
	v_mfma_f32_16x16x32_bf16 v[6:9], v[166:169], v[206:209], v[6:9]
	v_mfma_f32_16x16x32_bf16 v[2:5], v[174:177], v[206:209], v[2:5]
	v_mfma_f32_16x16x32_bf16 v[50:53], v[170:173], v[186:189], v[50:53]
	v_mfma_f32_16x16x32_bf16 v[42:45], v[178:181], v[186:189], v[42:45]
	v_mfma_f32_16x16x32_bf16 v[34:37], v[170:173], v[194:197], v[34:37]
	v_mfma_f32_16x16x32_bf16 v[26:29], v[178:181], v[194:197], v[26:29]
	v_mfma_f32_16x16x32_bf16 v[18:21], v[170:173], v[202:205], v[18:21]
	v_mfma_f32_16x16x32_bf16 v[10:13], v[178:181], v[202:205], v[10:13]
	v_mfma_f32_16x16x32_bf16 v[6:9], v[170:173], v[224:227], v[6:9]
	v_mfma_f32_16x16x32_bf16 v[2:5], v[178:181], v[224:227], v[2:5]
	s_setprio 0
	s_barrier
	s_add_i32 s83, s83, 2
	s_add_u32 s52, s52, 0x100
	s_addc_u32 s53, s53, 0
	s_add_u32 s81, s81, 0x100
	s_addc_u32 s82, s82, 0
